# phase-0 row pass rewritten by hand: two stages of row loads in flight, DPP reductions (compiler loop kept for other grid sizes); ffn_fixup temps moved off v200
# speedup vs baseline: 1.0028x; 1.0028x over previous
.LBB0_37:
	s_ashr_i32 s0, s21, 3
	s_add_i32 s0, s23, s0
	s_ashr_i32 s1, s0, 31
	s_lshr_b32 s1, s1, 27
	s_add_i32 s1, s0, s1
	s_ashr_i32 s21, s1, 5
	s_lshl_b32 s37, s21, 3
	s_sub_i32 s21, 0x80, s37
	s_min_i32 s21, s21, 8
	s_abs_i32 s21, s21
	v_cvt_f32_u32_e32 v0, s21
	s_sub_i32 s22, 0, s21
	s_andn2_b32 s1, s1, 31
	s_sub_i32 s0, s0, s1
	v_rcp_iflag_f32_e32 v0, v0
	s_ashr_i32 s1, s0, 31
	s_abs_i32 s0, s0
	v_mul_f32_e32 v0, 0x4f7ffffe, v0
	v_cvt_u32_f32_e32 v0, v0
	s_nop 0
	v_readfirstlane_b32 s23, v0
	s_mul_i32 s22, s22, s23
	s_mul_hi_u32 s22, s23, s22
	s_add_i32 s23, s23, s22
	s_mul_hi_u32 s22, s0, s23
	s_mul_i32 s22, s22, s21
	s_sub_i32 s0, s0, s22
	s_sub_i32 s22, s0, s21
	s_cmp_ge_u32 s0, s21
	s_cselect_b32 s0, s22, s0
	s_sub_i32 s22, s0, s21
	s_cmp_ge_u32 s0, s21
	s_cselect_b32 s0, s22, s0
	s_xor_b32 s0, s0, s1
	s_sub_i32 s0, s0, s1
	s_add_i32 s37, s37, s0
	s_cmp_lg_u32 s37, s20
	s_cbranch_scc0 .LBB0_30
	v_cmp_gt_u32_e32 vcc, 0x160, v197
	s_and_saveexec_b64 s[0:1], vcc
	s_cbranch_execz .LBB0_29
	v_readlane_b32 s22, v252, 2
	v_readlane_b32 s23, v252, 3
	v_readlane_b32 s24, v252, 4
	v_readlane_b32 s25, v252, 5
	v_readlane_b32 s2, v252, 14
	v_readlane_b32 s3, v252, 15
	s_lshl_b32 s42, s37, 2
	v_lshlrev_b32_e32 v236, 4, v197
	v_lshlrev_b32_e32 v240, 5, v197
	v_add_u32_e32 v237, 0x1600, v236
	v_add_u32_e32 v238, 0x2c00, v236
	v_add_u32_e32 v239, 0x4200, v236
	v_add_u32_e32 v241, 0x5800, v240
	v_add_u32_e32 v242, 0xb000, v240
	v_add_u32_e32 v243, 0x2c00, v240
	v_add_u32_e32 v244, 0x2c00, v241
	v_add_u32_e32 v245, 0x2c00, v242
	global_load_dwordx4 v[4:7], v240, s[24:25]
	global_load_dwordx4 v[8:11], v240, s[24:25] offset:16
	global_load_dwordx4 v[12:15], v243, s[24:25]
	global_load_dwordx4 v[16:19], v243, s[24:25] offset:16
	global_load_dwordx4 v[20:23], v240, s[22:23]
	global_load_dwordx4 v[24:27], v240, s[22:23] offset:16
	global_load_dwordx4 v[28:31], v241, s[22:23]
	global_load_dwordx4 v[32:35], v241, s[22:23] offset:16
	global_load_dwordx4 v[36:39], v242, s[22:23]
	global_load_dwordx4 v[40:43], v242, s[22:23] offset:16
	global_load_dwordx4 v[44:47], v243, s[22:23]
	global_load_dwordx4 v[48:51], v243, s[22:23] offset:16
	global_load_dwordx4 v[52:55], v244, s[22:23]
	global_load_dwordx4 v[56:59], v244, s[22:23] offset:16
	global_load_dwordx4 v[60:63], v245, s[22:23]
	global_load_dwordx4 v[64:67], v245, s[22:23] offset:16
	s_add_i32 s40, s42, 0
	s_mul_i32 s41, s40, 0xb000
	s_add_u32 s20, s56, s41
	s_addc_u32 s21, s57, 0
	s_add_u32 s26, s20, 0xffff5000
	s_addc_u32 s27, s21, -1
	s_add_u32 s20, s20, 0x5800
	s_addc_u32 s21, s21, 0
	s_and_b32 s41, s37, 15
	s_cmp_eq_u32 s41, 0
	s_cselect_b32 s26, s2, s26
	s_cselect_b32 s27, s3, s27
	global_load_dwordx4 v[68:71], v236, s[26:27]
	global_load_dwordx4 v[72:75], v238, s[26:27]
	global_load_dwordx4 v[76:79], v236, s[20:21]
	global_load_dwordx4 v[80:83], v238, s[20:21]
	global_load_dwordx4 v[84:87], v237, s[26:27]
	global_load_dwordx4 v[88:91], v239, s[26:27]
	global_load_dwordx4 v[92:95], v237, s[20:21]
	global_load_dwordx4 v[96:99], v239, s[20:21]
	s_add_i32 s40, s42, 1
	s_mul_i32 s41, s40, 0xb000
	s_add_u32 s20, s56, s41
	s_addc_u32 s21, s57, 0
	s_add_u32 s26, s20, 0xffff5000
	s_addc_u32 s27, s21, -1
	s_add_u32 s20, s20, 0x5800
	s_addc_u32 s21, s21, 0
	global_load_dwordx4 v[100:103], v236, s[26:27]
	global_load_dwordx4 v[104:107], v238, s[26:27]
	global_load_dwordx4 v[108:111], v236, s[20:21]
	global_load_dwordx4 v[112:115], v238, s[20:21]
	global_load_dwordx4 v[116:119], v237, s[26:27]
	global_load_dwordx4 v[120:123], v239, s[26:27]
	global_load_dwordx4 v[124:127], v237, s[20:21]
	global_load_dwordx4 v[128:131], v239, s[20:21]
	s_add_i32 s40, s42, 2
	s_mul_i32 s41, s40, 0xb000
	s_add_u32 s20, s56, s41
	s_addc_u32 s21, s57, 0
	s_add_u32 s26, s20, 0xffff5000
	s_addc_u32 s27, s21, -1
	s_add_u32 s20, s20, 0x5800
	s_addc_u32 s21, s21, 0
	global_load_dwordx4 v[132:135], v236, s[26:27]
	global_load_dwordx4 v[136:139], v238, s[26:27]
	global_load_dwordx4 v[140:143], v236, s[20:21]
	global_load_dwordx4 v[144:147], v238, s[20:21]
	global_load_dwordx4 v[148:151], v237, s[26:27]
	global_load_dwordx4 v[152:155], v239, s[26:27]
	global_load_dwordx4 v[156:159], v237, s[20:21]
	global_load_dwordx4 v[160:163], v239, s[20:21]
	s_add_i32 s40, s42, 3
	s_mul_i32 s41, s40, 0xb000
	s_add_u32 s20, s56, s41
	s_addc_u32 s21, s57, 0
	s_add_u32 s26, s20, 0xffff5000
	s_addc_u32 s27, s21, -1
	s_add_u32 s20, s20, 0x5800
	s_addc_u32 s21, s21, 0
	global_load_dwordx4 v[164:167], v236, s[26:27]
	global_load_dwordx4 v[168:171], v238, s[26:27]
	global_load_dwordx4 v[172:175], v236, s[20:21]
	global_load_dwordx4 v[176:179], v238, s[20:21]
	global_load_dwordx4 v[180:183], v237, s[26:27]
	global_load_dwordx4 v[184:187], v239, s[26:27]
	global_load_dwordx4 v[188:191], v237, s[20:21]
	global_load_dwordx4 v[192:195], v239, s[20:21]
	s_mov_b32 s40, 0xbfb8aa3b
	s_mov_b32 s41, 0xbfb8aa3b
	s_waitcnt vmcnt(24)
	v_lshlrev_b32_e32 v202, 16, v68
	v_and_b32_e32 v203, 0xffff0000, v68
	v_lshlrev_b32_e32 v204, 16, v72
	v_and_b32_e32 v205, 0xffff0000, v72
	v_lshlrev_b32_e32 v206, 16, v76
	v_and_b32_e32 v207, 0xffff0000, v76
	v_lshlrev_b32_e32 v208, 16, v80
	v_and_b32_e32 v209, 0xffff0000, v80
	v_lshlrev_b32_e32 v210, 16, v84
	v_and_b32_e32 v211, 0xffff0000, v84
	v_lshlrev_b32_e32 v212, 16, v88
	v_and_b32_e32 v213, 0xffff0000, v88
	v_lshlrev_b32_e32 v214, 16, v92
	v_and_b32_e32 v215, 0xffff0000, v92
	v_lshlrev_b32_e32 v216, 16, v96
	v_and_b32_e32 v217, 0xffff0000, v96
	v_pk_fma_f32 v[246:247], v[36:37], v[206:207], v[4:5]
	v_pk_fma_f32 v[250:251], v[60:61], v[214:215], v[12:13]
	v_pk_fma_f32 v[248:249], v[36:37], v[208:209], v[4:5]
	v_pk_fma_f32 v[0:1], v[60:61], v[216:217], v[12:13]
	v_pk_fma_f32 v[246:247], v[28:29], v[204:205], v[246:247]
	v_pk_fma_f32 v[250:251], v[52:53], v[212:213], v[250:251]
	v_pk_fma_f32 v[248:249], v[28:29], v[206:207], v[248:249]
	v_pk_fma_f32 v[0:1], v[52:53], v[214:215], v[0:1]
	v_pk_fma_f32 v[246:247], v[20:21], v[202:203], v[246:247]
	v_pk_fma_f32 v[250:251], v[44:45], v[210:211], v[250:251]
	v_pk_fma_f32 v[248:249], v[20:21], v[204:205], v[248:249]
	v_pk_fma_f32 v[0:1], v[44:45], v[212:213], v[0:1]
	v_pk_mul_f32 v[202:203], v[246:247], s[40:41]
	v_pk_mul_f32 v[204:205], v[248:249], s[40:41]
	v_exp_f32_e32 v202, v202
	v_exp_f32_e32 v203, v203
	v_exp_f32_e32 v204, v204
	v_exp_f32_e32 v205, v205
	v_pk_mul_f32 v[250:251], v[250:251], v[246:247]
	v_pk_mul_f32 v[0:1], v[0:1], v[248:249]
	v_pk_add_f32 v[202:203], v[202:203], 1.0 op_sel_hi:[1,0]
	v_pk_add_f32 v[204:205], v[204:205], 1.0 op_sel_hi:[1,0]
	v_rcp_f32_e32 v202, v202
	v_rcp_f32_e32 v203, v203
	v_rcp_f32_e32 v204, v204
	v_rcp_f32_e32 v205, v205
	s_nop 0
	v_pk_mul_f32 v[250:251], v[250:251], v[202:203]
	v_pk_mul_f32 v[0:1], v[0:1], v[204:205]
	v_cvt_pk_bf16_f32 v68, v250, v251
	v_cvt_pk_bf16_f32 v72, v0, v1
	v_lshlrev_b32_e32 v202, 16, v69
	v_and_b32_e32 v203, 0xffff0000, v69
	v_lshlrev_b32_e32 v204, 16, v73
	v_and_b32_e32 v205, 0xffff0000, v73
	v_lshlrev_b32_e32 v206, 16, v77
	v_and_b32_e32 v207, 0xffff0000, v77
	v_lshlrev_b32_e32 v208, 16, v81
	v_and_b32_e32 v209, 0xffff0000, v81
	v_lshlrev_b32_e32 v210, 16, v85
	v_and_b32_e32 v211, 0xffff0000, v85
	v_lshlrev_b32_e32 v212, 16, v89
	v_and_b32_e32 v213, 0xffff0000, v89
	v_lshlrev_b32_e32 v214, 16, v93
	v_and_b32_e32 v215, 0xffff0000, v93
	v_lshlrev_b32_e32 v216, 16, v97
	v_and_b32_e32 v217, 0xffff0000, v97
	v_pk_fma_f32 v[246:247], v[38:39], v[206:207], v[6:7]
	v_pk_fma_f32 v[250:251], v[62:63], v[214:215], v[14:15]
	v_pk_fma_f32 v[248:249], v[38:39], v[208:209], v[6:7]
	v_pk_fma_f32 v[0:1], v[62:63], v[216:217], v[14:15]
	v_pk_fma_f32 v[246:247], v[30:31], v[204:205], v[246:247]
	v_pk_fma_f32 v[250:251], v[54:55], v[212:213], v[250:251]
	v_pk_fma_f32 v[248:249], v[30:31], v[206:207], v[248:249]
	v_pk_fma_f32 v[0:1], v[54:55], v[214:215], v[0:1]
	v_pk_fma_f32 v[246:247], v[22:23], v[202:203], v[246:247]
	v_pk_fma_f32 v[250:251], v[46:47], v[210:211], v[250:251]
	v_pk_fma_f32 v[248:249], v[22:23], v[204:205], v[248:249]
	v_pk_fma_f32 v[0:1], v[46:47], v[212:213], v[0:1]
	v_pk_mul_f32 v[202:203], v[246:247], s[40:41]
	v_pk_mul_f32 v[204:205], v[248:249], s[40:41]
	v_exp_f32_e32 v202, v202
	v_exp_f32_e32 v203, v203
	v_exp_f32_e32 v204, v204
	v_exp_f32_e32 v205, v205
	v_pk_mul_f32 v[250:251], v[250:251], v[246:247]
	v_pk_mul_f32 v[0:1], v[0:1], v[248:249]
	v_pk_add_f32 v[202:203], v[202:203], 1.0 op_sel_hi:[1,0]
	v_pk_add_f32 v[204:205], v[204:205], 1.0 op_sel_hi:[1,0]
	v_rcp_f32_e32 v202, v202
	v_rcp_f32_e32 v203, v203
	v_rcp_f32_e32 v204, v204
	v_rcp_f32_e32 v205, v205
	s_nop 0
	v_pk_mul_f32 v[250:251], v[250:251], v[202:203]
	v_pk_mul_f32 v[0:1], v[0:1], v[204:205]
	v_cvt_pk_bf16_f32 v69, v250, v251
	v_cvt_pk_bf16_f32 v73, v0, v1
	v_lshlrev_b32_e32 v202, 16, v70
	v_and_b32_e32 v203, 0xffff0000, v70
	v_lshlrev_b32_e32 v204, 16, v74
	v_and_b32_e32 v205, 0xffff0000, v74
	v_lshlrev_b32_e32 v206, 16, v78
	v_and_b32_e32 v207, 0xffff0000, v78
	v_lshlrev_b32_e32 v208, 16, v82
	v_and_b32_e32 v209, 0xffff0000, v82
	v_lshlrev_b32_e32 v210, 16, v86
	v_and_b32_e32 v211, 0xffff0000, v86
	v_lshlrev_b32_e32 v212, 16, v90
	v_and_b32_e32 v213, 0xffff0000, v90
	v_lshlrev_b32_e32 v214, 16, v94
	v_and_b32_e32 v215, 0xffff0000, v94
	v_lshlrev_b32_e32 v216, 16, v98
	v_and_b32_e32 v217, 0xffff0000, v98
	v_pk_fma_f32 v[246:247], v[40:41], v[206:207], v[8:9]
	v_pk_fma_f32 v[250:251], v[64:65], v[214:215], v[16:17]
	v_pk_fma_f32 v[248:249], v[40:41], v[208:209], v[8:9]
	v_pk_fma_f32 v[0:1], v[64:65], v[216:217], v[16:17]
	v_pk_fma_f32 v[246:247], v[32:33], v[204:205], v[246:247]
	v_pk_fma_f32 v[250:251], v[56:57], v[212:213], v[250:251]
	v_pk_fma_f32 v[248:249], v[32:33], v[206:207], v[248:249]
	v_pk_fma_f32 v[0:1], v[56:57], v[214:215], v[0:1]
	v_pk_fma_f32 v[246:247], v[24:25], v[202:203], v[246:247]
	v_pk_fma_f32 v[250:251], v[48:49], v[210:211], v[250:251]
	v_pk_fma_f32 v[248:249], v[24:25], v[204:205], v[248:249]
	v_pk_fma_f32 v[0:1], v[48:49], v[212:213], v[0:1]
	v_pk_mul_f32 v[202:203], v[246:247], s[40:41]
	v_pk_mul_f32 v[204:205], v[248:249], s[40:41]
	v_exp_f32_e32 v202, v202
	v_exp_f32_e32 v203, v203
	v_exp_f32_e32 v204, v204
	v_exp_f32_e32 v205, v205
	v_pk_mul_f32 v[250:251], v[250:251], v[246:247]
	v_pk_mul_f32 v[0:1], v[0:1], v[248:249]
	v_pk_add_f32 v[202:203], v[202:203], 1.0 op_sel_hi:[1,0]
	v_pk_add_f32 v[204:205], v[204:205], 1.0 op_sel_hi:[1,0]
	v_rcp_f32_e32 v202, v202
	v_rcp_f32_e32 v203, v203
	v_rcp_f32_e32 v204, v204
	v_rcp_f32_e32 v205, v205
	s_nop 0
	v_pk_mul_f32 v[250:251], v[250:251], v[202:203]
	v_pk_mul_f32 v[0:1], v[0:1], v[204:205]
	v_cvt_pk_bf16_f32 v70, v250, v251
	v_cvt_pk_bf16_f32 v74, v0, v1
	v_lshlrev_b32_e32 v202, 16, v71
	v_and_b32_e32 v203, 0xffff0000, v71
	v_lshlrev_b32_e32 v204, 16, v75
	v_and_b32_e32 v205, 0xffff0000, v75
	v_lshlrev_b32_e32 v206, 16, v79
	v_and_b32_e32 v207, 0xffff0000, v79
	v_lshlrev_b32_e32 v208, 16, v83
	v_and_b32_e32 v209, 0xffff0000, v83
	v_lshlrev_b32_e32 v210, 16, v87
	v_and_b32_e32 v211, 0xffff0000, v87
	v_lshlrev_b32_e32 v212, 16, v91
	v_and_b32_e32 v213, 0xffff0000, v91
	v_lshlrev_b32_e32 v214, 16, v95
	v_and_b32_e32 v215, 0xffff0000, v95
	v_lshlrev_b32_e32 v216, 16, v99
	v_and_b32_e32 v217, 0xffff0000, v99
	v_pk_fma_f32 v[246:247], v[42:43], v[206:207], v[10:11]
	v_pk_fma_f32 v[250:251], v[66:67], v[214:215], v[18:19]
	v_pk_fma_f32 v[248:249], v[42:43], v[208:209], v[10:11]
	v_pk_fma_f32 v[0:1], v[66:67], v[216:217], v[18:19]
	v_pk_fma_f32 v[246:247], v[34:35], v[204:205], v[246:247]
	v_pk_fma_f32 v[250:251], v[58:59], v[212:213], v[250:251]
	v_pk_fma_f32 v[248:249], v[34:35], v[206:207], v[248:249]
	v_pk_fma_f32 v[0:1], v[58:59], v[214:215], v[0:1]
	v_pk_fma_f32 v[246:247], v[26:27], v[202:203], v[246:247]
	v_pk_fma_f32 v[250:251], v[50:51], v[210:211], v[250:251]
	v_pk_fma_f32 v[248:249], v[26:27], v[204:205], v[248:249]
	v_pk_fma_f32 v[0:1], v[50:51], v[212:213], v[0:1]
	v_pk_mul_f32 v[202:203], v[246:247], s[40:41]
	v_pk_mul_f32 v[204:205], v[248:249], s[40:41]
	v_exp_f32_e32 v202, v202
	v_exp_f32_e32 v203, v203
	v_exp_f32_e32 v204, v204
	v_exp_f32_e32 v205, v205
	v_pk_mul_f32 v[250:251], v[250:251], v[246:247]
	v_pk_mul_f32 v[0:1], v[0:1], v[248:249]
	v_pk_add_f32 v[202:203], v[202:203], 1.0 op_sel_hi:[1,0]
	v_pk_add_f32 v[204:205], v[204:205], 1.0 op_sel_hi:[1,0]
	v_rcp_f32_e32 v202, v202
	v_rcp_f32_e32 v203, v203
	v_rcp_f32_e32 v204, v204
	v_rcp_f32_e32 v205, v205
	s_nop 0
	v_pk_mul_f32 v[250:251], v[250:251], v[202:203]
	v_pk_mul_f32 v[0:1], v[0:1], v[204:205]
	v_cvt_pk_bf16_f32 v71, v250, v251
	v_cvt_pk_bf16_f32 v75, v0, v1
	s_add_i32 s38, s42, 0
	s_mul_i32 s39, s38, 0x58000
	s_add_u32 s38, s82, s39
	s_addc_u32 s39, s83, 0
	global_store_dwordx4 v236, v[68:71], s[38:39]
	global_store_dwordx4 v237, v[72:75], s[38:39]
	s_waitcnt vmcnt(18)
	v_lshlrev_b32_e32 v202, 16, v100
	v_and_b32_e32 v203, 0xffff0000, v100
	v_lshlrev_b32_e32 v204, 16, v104
	v_and_b32_e32 v205, 0xffff0000, v104
	v_lshlrev_b32_e32 v206, 16, v108
	v_and_b32_e32 v207, 0xffff0000, v108
	v_lshlrev_b32_e32 v208, 16, v112
	v_and_b32_e32 v209, 0xffff0000, v112
	v_lshlrev_b32_e32 v210, 16, v116
	v_and_b32_e32 v211, 0xffff0000, v116
	v_lshlrev_b32_e32 v212, 16, v120
	v_and_b32_e32 v213, 0xffff0000, v120
	v_lshlrev_b32_e32 v214, 16, v124
	v_and_b32_e32 v215, 0xffff0000, v124
	v_lshlrev_b32_e32 v216, 16, v128
	v_and_b32_e32 v217, 0xffff0000, v128
	v_pk_fma_f32 v[246:247], v[36:37], v[206:207], v[4:5]
	v_pk_fma_f32 v[250:251], v[60:61], v[214:215], v[12:13]
	v_pk_fma_f32 v[248:249], v[36:37], v[208:209], v[4:5]
	v_pk_fma_f32 v[0:1], v[60:61], v[216:217], v[12:13]
	v_pk_fma_f32 v[246:247], v[28:29], v[204:205], v[246:247]
	v_pk_fma_f32 v[250:251], v[52:53], v[212:213], v[250:251]
	v_pk_fma_f32 v[248:249], v[28:29], v[206:207], v[248:249]
	v_pk_fma_f32 v[0:1], v[52:53], v[214:215], v[0:1]
	v_pk_fma_f32 v[246:247], v[20:21], v[202:203], v[246:247]
	v_pk_fma_f32 v[250:251], v[44:45], v[210:211], v[250:251]
	v_pk_fma_f32 v[248:249], v[20:21], v[204:205], v[248:249]
	v_pk_fma_f32 v[0:1], v[44:45], v[212:213], v[0:1]
	v_pk_mul_f32 v[202:203], v[246:247], s[40:41]
	v_pk_mul_f32 v[204:205], v[248:249], s[40:41]
	v_exp_f32_e32 v202, v202
	v_exp_f32_e32 v203, v203
	v_exp_f32_e32 v204, v204
	v_exp_f32_e32 v205, v205
	v_pk_mul_f32 v[250:251], v[250:251], v[246:247]
	v_pk_mul_f32 v[0:1], v[0:1], v[248:249]
	v_pk_add_f32 v[202:203], v[202:203], 1.0 op_sel_hi:[1,0]
	v_pk_add_f32 v[204:205], v[204:205], 1.0 op_sel_hi:[1,0]
	v_rcp_f32_e32 v202, v202
	v_rcp_f32_e32 v203, v203
	v_rcp_f32_e32 v204, v204
	v_rcp_f32_e32 v205, v205
	s_nop 0
	v_pk_mul_f32 v[250:251], v[250:251], v[202:203]
	v_pk_mul_f32 v[0:1], v[0:1], v[204:205]
	v_cvt_pk_bf16_f32 v100, v250, v251
	v_cvt_pk_bf16_f32 v104, v0, v1
	v_lshlrev_b32_e32 v202, 16, v101
	v_and_b32_e32 v203, 0xffff0000, v101
	v_lshlrev_b32_e32 v204, 16, v105
	v_and_b32_e32 v205, 0xffff0000, v105
	v_lshlrev_b32_e32 v206, 16, v109
	v_and_b32_e32 v207, 0xffff0000, v109
	v_lshlrev_b32_e32 v208, 16, v113
	v_and_b32_e32 v209, 0xffff0000, v113
	v_lshlrev_b32_e32 v210, 16, v117
	v_and_b32_e32 v211, 0xffff0000, v117
	v_lshlrev_b32_e32 v212, 16, v121
	v_and_b32_e32 v213, 0xffff0000, v121
	v_lshlrev_b32_e32 v214, 16, v125
	v_and_b32_e32 v215, 0xffff0000, v125
	v_lshlrev_b32_e32 v216, 16, v129
	v_and_b32_e32 v217, 0xffff0000, v129
	v_pk_fma_f32 v[246:247], v[38:39], v[206:207], v[6:7]
	v_pk_fma_f32 v[250:251], v[62:63], v[214:215], v[14:15]
	v_pk_fma_f32 v[248:249], v[38:39], v[208:209], v[6:7]
	v_pk_fma_f32 v[0:1], v[62:63], v[216:217], v[14:15]
	v_pk_fma_f32 v[246:247], v[30:31], v[204:205], v[246:247]
	v_pk_fma_f32 v[250:251], v[54:55], v[212:213], v[250:251]
	v_pk_fma_f32 v[248:249], v[30:31], v[206:207], v[248:249]
	v_pk_fma_f32 v[0:1], v[54:55], v[214:215], v[0:1]
	v_pk_fma_f32 v[246:247], v[22:23], v[202:203], v[246:247]
	v_pk_fma_f32 v[250:251], v[46:47], v[210:211], v[250:251]
	v_pk_fma_f32 v[248:249], v[22:23], v[204:205], v[248:249]
	v_pk_fma_f32 v[0:1], v[46:47], v[212:213], v[0:1]
	v_pk_mul_f32 v[202:203], v[246:247], s[40:41]
	v_pk_mul_f32 v[204:205], v[248:249], s[40:41]
	v_exp_f32_e32 v202, v202
	v_exp_f32_e32 v203, v203
	v_exp_f32_e32 v204, v204
	v_exp_f32_e32 v205, v205
	v_pk_mul_f32 v[250:251], v[250:251], v[246:247]
	v_pk_mul_f32 v[0:1], v[0:1], v[248:249]
	v_pk_add_f32 v[202:203], v[202:203], 1.0 op_sel_hi:[1,0]
	v_pk_add_f32 v[204:205], v[204:205], 1.0 op_sel_hi:[1,0]
	v_rcp_f32_e32 v202, v202
	v_rcp_f32_e32 v203, v203
	v_rcp_f32_e32 v204, v204
	v_rcp_f32_e32 v205, v205
	s_nop 0
	v_pk_mul_f32 v[250:251], v[250:251], v[202:203]
	v_pk_mul_f32 v[0:1], v[0:1], v[204:205]
	v_cvt_pk_bf16_f32 v101, v250, v251
	v_cvt_pk_bf16_f32 v105, v0, v1
	v_lshlrev_b32_e32 v202, 16, v102
	v_and_b32_e32 v203, 0xffff0000, v102
	v_lshlrev_b32_e32 v204, 16, v106
	v_and_b32_e32 v205, 0xffff0000, v106
	v_lshlrev_b32_e32 v206, 16, v110
	v_and_b32_e32 v207, 0xffff0000, v110
	v_lshlrev_b32_e32 v208, 16, v114
	v_and_b32_e32 v209, 0xffff0000, v114
	v_lshlrev_b32_e32 v210, 16, v118
	v_and_b32_e32 v211, 0xffff0000, v118
	v_lshlrev_b32_e32 v212, 16, v122
	v_and_b32_e32 v213, 0xffff0000, v122
	v_lshlrev_b32_e32 v214, 16, v126
	v_and_b32_e32 v215, 0xffff0000, v126
	v_lshlrev_b32_e32 v216, 16, v130
	v_and_b32_e32 v217, 0xffff0000, v130
	v_pk_fma_f32 v[246:247], v[40:41], v[206:207], v[8:9]
	v_pk_fma_f32 v[250:251], v[64:65], v[214:215], v[16:17]
	v_pk_fma_f32 v[248:249], v[40:41], v[208:209], v[8:9]
	v_pk_fma_f32 v[0:1], v[64:65], v[216:217], v[16:17]
	v_pk_fma_f32 v[246:247], v[32:33], v[204:205], v[246:247]
	v_pk_fma_f32 v[250:251], v[56:57], v[212:213], v[250:251]
	v_pk_fma_f32 v[248:249], v[32:33], v[206:207], v[248:249]
	v_pk_fma_f32 v[0:1], v[56:57], v[214:215], v[0:1]
	v_pk_fma_f32 v[246:247], v[24:25], v[202:203], v[246:247]
	v_pk_fma_f32 v[250:251], v[48:49], v[210:211], v[250:251]
	v_pk_fma_f32 v[248:249], v[24:25], v[204:205], v[248:249]
	v_pk_fma_f32 v[0:1], v[48:49], v[212:213], v[0:1]
	v_pk_mul_f32 v[202:203], v[246:247], s[40:41]
	v_pk_mul_f32 v[204:205], v[248:249], s[40:41]
	v_exp_f32_e32 v202, v202
	v_exp_f32_e32 v203, v203
	v_exp_f32_e32 v204, v204
	v_exp_f32_e32 v205, v205
	v_pk_mul_f32 v[250:251], v[250:251], v[246:247]
	v_pk_mul_f32 v[0:1], v[0:1], v[248:249]
	v_pk_add_f32 v[202:203], v[202:203], 1.0 op_sel_hi:[1,0]
	v_pk_add_f32 v[204:205], v[204:205], 1.0 op_sel_hi:[1,0]
	v_rcp_f32_e32 v202, v202
	v_rcp_f32_e32 v203, v203
	v_rcp_f32_e32 v204, v204
	v_rcp_f32_e32 v205, v205
	s_nop 0
	v_pk_mul_f32 v[250:251], v[250:251], v[202:203]
	v_pk_mul_f32 v[0:1], v[0:1], v[204:205]
	v_cvt_pk_bf16_f32 v102, v250, v251
	v_cvt_pk_bf16_f32 v106, v0, v1
	v_lshlrev_b32_e32 v202, 16, v103
	v_and_b32_e32 v203, 0xffff0000, v103
	v_lshlrev_b32_e32 v204, 16, v107
	v_and_b32_e32 v205, 0xffff0000, v107
	v_lshlrev_b32_e32 v206, 16, v111
	v_and_b32_e32 v207, 0xffff0000, v111
	v_lshlrev_b32_e32 v208, 16, v115
	v_and_b32_e32 v209, 0xffff0000, v115
	v_lshlrev_b32_e32 v210, 16, v119
	v_and_b32_e32 v211, 0xffff0000, v119
	v_lshlrev_b32_e32 v212, 16, v123
	v_and_b32_e32 v213, 0xffff0000, v123
	v_lshlrev_b32_e32 v214, 16, v127
	v_and_b32_e32 v215, 0xffff0000, v127
	v_lshlrev_b32_e32 v216, 16, v131
	v_and_b32_e32 v217, 0xffff0000, v131
	v_pk_fma_f32 v[246:247], v[42:43], v[206:207], v[10:11]
	v_pk_fma_f32 v[250:251], v[66:67], v[214:215], v[18:19]
	v_pk_fma_f32 v[248:249], v[42:43], v[208:209], v[10:11]
	v_pk_fma_f32 v[0:1], v[66:67], v[216:217], v[18:19]
	v_pk_fma_f32 v[246:247], v[34:35], v[204:205], v[246:247]
	v_pk_fma_f32 v[250:251], v[58:59], v[212:213], v[250:251]
	v_pk_fma_f32 v[248:249], v[34:35], v[206:207], v[248:249]
	v_pk_fma_f32 v[0:1], v[58:59], v[214:215], v[0:1]
	v_pk_fma_f32 v[246:247], v[26:27], v[202:203], v[246:247]
	v_pk_fma_f32 v[250:251], v[50:51], v[210:211], v[250:251]
	v_pk_fma_f32 v[248:249], v[26:27], v[204:205], v[248:249]
	v_pk_fma_f32 v[0:1], v[50:51], v[212:213], v[0:1]
	v_pk_mul_f32 v[202:203], v[246:247], s[40:41]
	v_pk_mul_f32 v[204:205], v[248:249], s[40:41]
	v_exp_f32_e32 v202, v202
	v_exp_f32_e32 v203, v203
	v_exp_f32_e32 v204, v204
	v_exp_f32_e32 v205, v205
	v_pk_mul_f32 v[250:251], v[250:251], v[246:247]
	v_pk_mul_f32 v[0:1], v[0:1], v[248:249]
	v_pk_add_f32 v[202:203], v[202:203], 1.0 op_sel_hi:[1,0]
	v_pk_add_f32 v[204:205], v[204:205], 1.0 op_sel_hi:[1,0]
	v_rcp_f32_e32 v202, v202
	v_rcp_f32_e32 v203, v203
	v_rcp_f32_e32 v204, v204
	v_rcp_f32_e32 v205, v205
	s_nop 0
	v_pk_mul_f32 v[250:251], v[250:251], v[202:203]
	v_pk_mul_f32 v[0:1], v[0:1], v[204:205]
	v_cvt_pk_bf16_f32 v103, v250, v251
	v_cvt_pk_bf16_f32 v107, v0, v1
	s_add_i32 s38, s42, 1
	s_mul_i32 s39, s38, 0x58000
	s_add_u32 s38, s82, s39
	s_addc_u32 s39, s83, 0
	global_store_dwordx4 v236, v[100:103], s[38:39]
	global_store_dwordx4 v237, v[104:107], s[38:39]
	s_waitcnt vmcnt(12)
	v_lshlrev_b32_e32 v202, 16, v132
	v_and_b32_e32 v203, 0xffff0000, v132
	v_lshlrev_b32_e32 v204, 16, v136
	v_and_b32_e32 v205, 0xffff0000, v136
	v_lshlrev_b32_e32 v206, 16, v140
	v_and_b32_e32 v207, 0xffff0000, v140
	v_lshlrev_b32_e32 v208, 16, v144
	v_and_b32_e32 v209, 0xffff0000, v144
	v_lshlrev_b32_e32 v210, 16, v148
	v_and_b32_e32 v211, 0xffff0000, v148
	v_lshlrev_b32_e32 v212, 16, v152
	v_and_b32_e32 v213, 0xffff0000, v152
	v_lshlrev_b32_e32 v214, 16, v156
	v_and_b32_e32 v215, 0xffff0000, v156
	v_lshlrev_b32_e32 v216, 16, v160
	v_and_b32_e32 v217, 0xffff0000, v160
	v_pk_fma_f32 v[246:247], v[36:37], v[206:207], v[4:5]
	v_pk_fma_f32 v[250:251], v[60:61], v[214:215], v[12:13]
	v_pk_fma_f32 v[248:249], v[36:37], v[208:209], v[4:5]
	v_pk_fma_f32 v[0:1], v[60:61], v[216:217], v[12:13]
	v_pk_fma_f32 v[246:247], v[28:29], v[204:205], v[246:247]
	v_pk_fma_f32 v[250:251], v[52:53], v[212:213], v[250:251]
	v_pk_fma_f32 v[248:249], v[28:29], v[206:207], v[248:249]
	v_pk_fma_f32 v[0:1], v[52:53], v[214:215], v[0:1]
	v_pk_fma_f32 v[246:247], v[20:21], v[202:203], v[246:247]
	v_pk_fma_f32 v[250:251], v[44:45], v[210:211], v[250:251]
	v_pk_fma_f32 v[248:249], v[20:21], v[204:205], v[248:249]
	v_pk_fma_f32 v[0:1], v[44:45], v[212:213], v[0:1]
	v_pk_mul_f32 v[202:203], v[246:247], s[40:41]
	v_pk_mul_f32 v[204:205], v[248:249], s[40:41]
	v_exp_f32_e32 v202, v202
	v_exp_f32_e32 v203, v203
	v_exp_f32_e32 v204, v204
	v_exp_f32_e32 v205, v205
	v_pk_mul_f32 v[250:251], v[250:251], v[246:247]
	v_pk_mul_f32 v[0:1], v[0:1], v[248:249]
	v_pk_add_f32 v[202:203], v[202:203], 1.0 op_sel_hi:[1,0]
	v_pk_add_f32 v[204:205], v[204:205], 1.0 op_sel_hi:[1,0]
	v_rcp_f32_e32 v202, v202
	v_rcp_f32_e32 v203, v203
	v_rcp_f32_e32 v204, v204
	v_rcp_f32_e32 v205, v205
	s_nop 0
	v_pk_mul_f32 v[250:251], v[250:251], v[202:203]
	v_pk_mul_f32 v[0:1], v[0:1], v[204:205]
	v_cvt_pk_bf16_f32 v132, v250, v251
	v_cvt_pk_bf16_f32 v136, v0, v1
	v_lshlrev_b32_e32 v202, 16, v133
	v_and_b32_e32 v203, 0xffff0000, v133
	v_lshlrev_b32_e32 v204, 16, v137
	v_and_b32_e32 v205, 0xffff0000, v137
	v_lshlrev_b32_e32 v206, 16, v141
	v_and_b32_e32 v207, 0xffff0000, v141
	v_lshlrev_b32_e32 v208, 16, v145
	v_and_b32_e32 v209, 0xffff0000, v145
	v_lshlrev_b32_e32 v210, 16, v149
	v_and_b32_e32 v211, 0xffff0000, v149
	v_lshlrev_b32_e32 v212, 16, v153
	v_and_b32_e32 v213, 0xffff0000, v153
	v_lshlrev_b32_e32 v214, 16, v157
	v_and_b32_e32 v215, 0xffff0000, v157
	v_lshlrev_b32_e32 v216, 16, v161
	v_and_b32_e32 v217, 0xffff0000, v161
	v_pk_fma_f32 v[246:247], v[38:39], v[206:207], v[6:7]
	v_pk_fma_f32 v[250:251], v[62:63], v[214:215], v[14:15]
	v_pk_fma_f32 v[248:249], v[38:39], v[208:209], v[6:7]
	v_pk_fma_f32 v[0:1], v[62:63], v[216:217], v[14:15]
	v_pk_fma_f32 v[246:247], v[30:31], v[204:205], v[246:247]
	v_pk_fma_f32 v[250:251], v[54:55], v[212:213], v[250:251]
	v_pk_fma_f32 v[248:249], v[30:31], v[206:207], v[248:249]
	v_pk_fma_f32 v[0:1], v[54:55], v[214:215], v[0:1]
	v_pk_fma_f32 v[246:247], v[22:23], v[202:203], v[246:247]
	v_pk_fma_f32 v[250:251], v[46:47], v[210:211], v[250:251]
	v_pk_fma_f32 v[248:249], v[22:23], v[204:205], v[248:249]
	v_pk_fma_f32 v[0:1], v[46:47], v[212:213], v[0:1]
	v_pk_mul_f32 v[202:203], v[246:247], s[40:41]
	v_pk_mul_f32 v[204:205], v[248:249], s[40:41]
	v_exp_f32_e32 v202, v202
	v_exp_f32_e32 v203, v203
	v_exp_f32_e32 v204, v204
	v_exp_f32_e32 v205, v205
	v_pk_mul_f32 v[250:251], v[250:251], v[246:247]
	v_pk_mul_f32 v[0:1], v[0:1], v[248:249]
	v_pk_add_f32 v[202:203], v[202:203], 1.0 op_sel_hi:[1,0]
	v_pk_add_f32 v[204:205], v[204:205], 1.0 op_sel_hi:[1,0]
	v_rcp_f32_e32 v202, v202
	v_rcp_f32_e32 v203, v203
	v_rcp_f32_e32 v204, v204
	v_rcp_f32_e32 v205, v205
	s_nop 0
	v_pk_mul_f32 v[250:251], v[250:251], v[202:203]
	v_pk_mul_f32 v[0:1], v[0:1], v[204:205]
	v_cvt_pk_bf16_f32 v133, v250, v251
	v_cvt_pk_bf16_f32 v137, v0, v1
	v_lshlrev_b32_e32 v202, 16, v134
	v_and_b32_e32 v203, 0xffff0000, v134
	v_lshlrev_b32_e32 v204, 16, v138
	v_and_b32_e32 v205, 0xffff0000, v138
	v_lshlrev_b32_e32 v206, 16, v142
	v_and_b32_e32 v207, 0xffff0000, v142
	v_lshlrev_b32_e32 v208, 16, v146
	v_and_b32_e32 v209, 0xffff0000, v146
	v_lshlrev_b32_e32 v210, 16, v150
	v_and_b32_e32 v211, 0xffff0000, v150
	v_lshlrev_b32_e32 v212, 16, v154
	v_and_b32_e32 v213, 0xffff0000, v154
	v_lshlrev_b32_e32 v214, 16, v158
	v_and_b32_e32 v215, 0xffff0000, v158
	v_lshlrev_b32_e32 v216, 16, v162
	v_and_b32_e32 v217, 0xffff0000, v162
	v_pk_fma_f32 v[246:247], v[40:41], v[206:207], v[8:9]
	v_pk_fma_f32 v[250:251], v[64:65], v[214:215], v[16:17]
	v_pk_fma_f32 v[248:249], v[40:41], v[208:209], v[8:9]
	v_pk_fma_f32 v[0:1], v[64:65], v[216:217], v[16:17]
	v_pk_fma_f32 v[246:247], v[32:33], v[204:205], v[246:247]
	v_pk_fma_f32 v[250:251], v[56:57], v[212:213], v[250:251]
	v_pk_fma_f32 v[248:249], v[32:33], v[206:207], v[248:249]
	v_pk_fma_f32 v[0:1], v[56:57], v[214:215], v[0:1]
	v_pk_fma_f32 v[246:247], v[24:25], v[202:203], v[246:247]
	v_pk_fma_f32 v[250:251], v[48:49], v[210:211], v[250:251]
	v_pk_fma_f32 v[248:249], v[24:25], v[204:205], v[248:249]
	v_pk_fma_f32 v[0:1], v[48:49], v[212:213], v[0:1]
	v_pk_mul_f32 v[202:203], v[246:247], s[40:41]
	v_pk_mul_f32 v[204:205], v[248:249], s[40:41]
	v_exp_f32_e32 v202, v202
	v_exp_f32_e32 v203, v203
	v_exp_f32_e32 v204, v204
	v_exp_f32_e32 v205, v205
	v_pk_mul_f32 v[250:251], v[250:251], v[246:247]
	v_pk_mul_f32 v[0:1], v[0:1], v[248:249]
	v_pk_add_f32 v[202:203], v[202:203], 1.0 op_sel_hi:[1,0]
	v_pk_add_f32 v[204:205], v[204:205], 1.0 op_sel_hi:[1,0]
	v_rcp_f32_e32 v202, v202
	v_rcp_f32_e32 v203, v203
	v_rcp_f32_e32 v204, v204
	v_rcp_f32_e32 v205, v205
	s_nop 0
	v_pk_mul_f32 v[250:251], v[250:251], v[202:203]
	v_pk_mul_f32 v[0:1], v[0:1], v[204:205]
	v_cvt_pk_bf16_f32 v134, v250, v251
	v_cvt_pk_bf16_f32 v138, v0, v1
	v_lshlrev_b32_e32 v202, 16, v135
	v_and_b32_e32 v203, 0xffff0000, v135
	v_lshlrev_b32_e32 v204, 16, v139
	v_and_b32_e32 v205, 0xffff0000, v139
	v_lshlrev_b32_e32 v206, 16, v143
	v_and_b32_e32 v207, 0xffff0000, v143
	v_lshlrev_b32_e32 v208, 16, v147
	v_and_b32_e32 v209, 0xffff0000, v147
	v_lshlrev_b32_e32 v210, 16, v151
	v_and_b32_e32 v211, 0xffff0000, v151
	v_lshlrev_b32_e32 v212, 16, v155
	v_and_b32_e32 v213, 0xffff0000, v155
	v_lshlrev_b32_e32 v214, 16, v159
	v_and_b32_e32 v215, 0xffff0000, v159
	v_lshlrev_b32_e32 v216, 16, v163
	v_and_b32_e32 v217, 0xffff0000, v163
	v_pk_fma_f32 v[246:247], v[42:43], v[206:207], v[10:11]
	v_pk_fma_f32 v[250:251], v[66:67], v[214:215], v[18:19]
	v_pk_fma_f32 v[248:249], v[42:43], v[208:209], v[10:11]
	v_pk_fma_f32 v[0:1], v[66:67], v[216:217], v[18:19]
	v_pk_fma_f32 v[246:247], v[34:35], v[204:205], v[246:247]
	v_pk_fma_f32 v[250:251], v[58:59], v[212:213], v[250:251]
	v_pk_fma_f32 v[248:249], v[34:35], v[206:207], v[248:249]
	v_pk_fma_f32 v[0:1], v[58:59], v[214:215], v[0:1]
	v_pk_fma_f32 v[246:247], v[26:27], v[202:203], v[246:247]
	v_pk_fma_f32 v[250:251], v[50:51], v[210:211], v[250:251]
	v_pk_fma_f32 v[248:249], v[26:27], v[204:205], v[248:249]
	v_pk_fma_f32 v[0:1], v[50:51], v[212:213], v[0:1]
	v_pk_mul_f32 v[202:203], v[246:247], s[40:41]
	v_pk_mul_f32 v[204:205], v[248:249], s[40:41]
	v_exp_f32_e32 v202, v202
	v_exp_f32_e32 v203, v203
	v_exp_f32_e32 v204, v204
	v_exp_f32_e32 v205, v205
	v_pk_mul_f32 v[250:251], v[250:251], v[246:247]
	v_pk_mul_f32 v[0:1], v[0:1], v[248:249]
	v_pk_add_f32 v[202:203], v[202:203], 1.0 op_sel_hi:[1,0]
	v_pk_add_f32 v[204:205], v[204:205], 1.0 op_sel_hi:[1,0]
	v_rcp_f32_e32 v202, v202
	v_rcp_f32_e32 v203, v203
	v_rcp_f32_e32 v204, v204
	v_rcp_f32_e32 v205, v205
	s_nop 0
	v_pk_mul_f32 v[250:251], v[250:251], v[202:203]
	v_pk_mul_f32 v[0:1], v[0:1], v[204:205]
	v_cvt_pk_bf16_f32 v135, v250, v251
	v_cvt_pk_bf16_f32 v139, v0, v1
	s_add_i32 s38, s42, 2
	s_mul_i32 s39, s38, 0x58000
	s_add_u32 s38, s82, s39
	s_addc_u32 s39, s83, 0
	global_store_dwordx4 v236, v[132:135], s[38:39]
	global_store_dwordx4 v237, v[136:139], s[38:39]
	s_waitcnt vmcnt(6)
	v_lshlrev_b32_e32 v202, 16, v164
	v_and_b32_e32 v203, 0xffff0000, v164
	v_lshlrev_b32_e32 v204, 16, v168
	v_and_b32_e32 v205, 0xffff0000, v168
	v_lshlrev_b32_e32 v206, 16, v172
	v_and_b32_e32 v207, 0xffff0000, v172
	v_lshlrev_b32_e32 v208, 16, v176
	v_and_b32_e32 v209, 0xffff0000, v176
	v_lshlrev_b32_e32 v210, 16, v180
	v_and_b32_e32 v211, 0xffff0000, v180
	v_lshlrev_b32_e32 v212, 16, v184
	v_and_b32_e32 v213, 0xffff0000, v184
	v_lshlrev_b32_e32 v214, 16, v188
	v_and_b32_e32 v215, 0xffff0000, v188
	v_lshlrev_b32_e32 v216, 16, v192
	v_and_b32_e32 v217, 0xffff0000, v192
	v_pk_fma_f32 v[246:247], v[36:37], v[206:207], v[4:5]
	v_pk_fma_f32 v[250:251], v[60:61], v[214:215], v[12:13]
	v_pk_fma_f32 v[248:249], v[36:37], v[208:209], v[4:5]
	v_pk_fma_f32 v[0:1], v[60:61], v[216:217], v[12:13]
	v_pk_fma_f32 v[246:247], v[28:29], v[204:205], v[246:247]
	v_pk_fma_f32 v[250:251], v[52:53], v[212:213], v[250:251]
	v_pk_fma_f32 v[248:249], v[28:29], v[206:207], v[248:249]
	v_pk_fma_f32 v[0:1], v[52:53], v[214:215], v[0:1]
	v_pk_fma_f32 v[246:247], v[20:21], v[202:203], v[246:247]
	v_pk_fma_f32 v[250:251], v[44:45], v[210:211], v[250:251]
	v_pk_fma_f32 v[248:249], v[20:21], v[204:205], v[248:249]
	v_pk_fma_f32 v[0:1], v[44:45], v[212:213], v[0:1]
	v_pk_mul_f32 v[202:203], v[246:247], s[40:41]
	v_pk_mul_f32 v[204:205], v[248:249], s[40:41]
	v_exp_f32_e32 v202, v202
	v_exp_f32_e32 v203, v203
	v_exp_f32_e32 v204, v204
	v_exp_f32_e32 v205, v205
	v_pk_mul_f32 v[250:251], v[250:251], v[246:247]
	v_pk_mul_f32 v[0:1], v[0:1], v[248:249]
	v_pk_add_f32 v[202:203], v[202:203], 1.0 op_sel_hi:[1,0]
	v_pk_add_f32 v[204:205], v[204:205], 1.0 op_sel_hi:[1,0]
	v_rcp_f32_e32 v202, v202
	v_rcp_f32_e32 v203, v203
	v_rcp_f32_e32 v204, v204
	v_rcp_f32_e32 v205, v205
	s_nop 0
	v_pk_mul_f32 v[250:251], v[250:251], v[202:203]
	v_pk_mul_f32 v[0:1], v[0:1], v[204:205]
	v_cvt_pk_bf16_f32 v164, v250, v251
	v_cvt_pk_bf16_f32 v168, v0, v1
	v_lshlrev_b32_e32 v202, 16, v165
	v_and_b32_e32 v203, 0xffff0000, v165
	v_lshlrev_b32_e32 v204, 16, v169
	v_and_b32_e32 v205, 0xffff0000, v169
	v_lshlrev_b32_e32 v206, 16, v173
	v_and_b32_e32 v207, 0xffff0000, v173
	v_lshlrev_b32_e32 v208, 16, v177
	v_and_b32_e32 v209, 0xffff0000, v177
	v_lshlrev_b32_e32 v210, 16, v181
	v_and_b32_e32 v211, 0xffff0000, v181
	v_lshlrev_b32_e32 v212, 16, v185
	v_and_b32_e32 v213, 0xffff0000, v185
	v_lshlrev_b32_e32 v214, 16, v189
	v_and_b32_e32 v215, 0xffff0000, v189
	v_lshlrev_b32_e32 v216, 16, v193
	v_and_b32_e32 v217, 0xffff0000, v193
	v_pk_fma_f32 v[246:247], v[38:39], v[206:207], v[6:7]
	v_pk_fma_f32 v[250:251], v[62:63], v[214:215], v[14:15]
	v_pk_fma_f32 v[248:249], v[38:39], v[208:209], v[6:7]
	v_pk_fma_f32 v[0:1], v[62:63], v[216:217], v[14:15]
	v_pk_fma_f32 v[246:247], v[30:31], v[204:205], v[246:247]
	v_pk_fma_f32 v[250:251], v[54:55], v[212:213], v[250:251]
	v_pk_fma_f32 v[248:249], v[30:31], v[206:207], v[248:249]
	v_pk_fma_f32 v[0:1], v[54:55], v[214:215], v[0:1]
	v_pk_fma_f32 v[246:247], v[22:23], v[202:203], v[246:247]
	v_pk_fma_f32 v[250:251], v[46:47], v[210:211], v[250:251]
	v_pk_fma_f32 v[248:249], v[22:23], v[204:205], v[248:249]
	v_pk_fma_f32 v[0:1], v[46:47], v[212:213], v[0:1]
	v_pk_mul_f32 v[202:203], v[246:247], s[40:41]
	v_pk_mul_f32 v[204:205], v[248:249], s[40:41]
	v_exp_f32_e32 v202, v202
	v_exp_f32_e32 v203, v203
	v_exp_f32_e32 v204, v204
	v_exp_f32_e32 v205, v205
	v_pk_mul_f32 v[250:251], v[250:251], v[246:247]
	v_pk_mul_f32 v[0:1], v[0:1], v[248:249]
	v_pk_add_f32 v[202:203], v[202:203], 1.0 op_sel_hi:[1,0]
	v_pk_add_f32 v[204:205], v[204:205], 1.0 op_sel_hi:[1,0]
	v_rcp_f32_e32 v202, v202
	v_rcp_f32_e32 v203, v203
	v_rcp_f32_e32 v204, v204
	v_rcp_f32_e32 v205, v205
	s_nop 0
	v_pk_mul_f32 v[250:251], v[250:251], v[202:203]
	v_pk_mul_f32 v[0:1], v[0:1], v[204:205]
	v_cvt_pk_bf16_f32 v165, v250, v251
	v_cvt_pk_bf16_f32 v169, v0, v1
	v_lshlrev_b32_e32 v202, 16, v166
	v_and_b32_e32 v203, 0xffff0000, v166
	v_lshlrev_b32_e32 v204, 16, v170
	v_and_b32_e32 v205, 0xffff0000, v170
	v_lshlrev_b32_e32 v206, 16, v174
	v_and_b32_e32 v207, 0xffff0000, v174
	v_lshlrev_b32_e32 v208, 16, v178
	v_and_b32_e32 v209, 0xffff0000, v178
	v_lshlrev_b32_e32 v210, 16, v182
	v_and_b32_e32 v211, 0xffff0000, v182
	v_lshlrev_b32_e32 v212, 16, v186
	v_and_b32_e32 v213, 0xffff0000, v186
	v_lshlrev_b32_e32 v214, 16, v190
	v_and_b32_e32 v215, 0xffff0000, v190
	v_lshlrev_b32_e32 v216, 16, v194
	v_and_b32_e32 v217, 0xffff0000, v194
	v_pk_fma_f32 v[246:247], v[40:41], v[206:207], v[8:9]
	v_pk_fma_f32 v[250:251], v[64:65], v[214:215], v[16:17]
	v_pk_fma_f32 v[248:249], v[40:41], v[208:209], v[8:9]
	v_pk_fma_f32 v[0:1], v[64:65], v[216:217], v[16:17]
	v_pk_fma_f32 v[246:247], v[32:33], v[204:205], v[246:247]
	v_pk_fma_f32 v[250:251], v[56:57], v[212:213], v[250:251]
	v_pk_fma_f32 v[248:249], v[32:33], v[206:207], v[248:249]
	v_pk_fma_f32 v[0:1], v[56:57], v[214:215], v[0:1]
	v_pk_fma_f32 v[246:247], v[24:25], v[202:203], v[246:247]
	v_pk_fma_f32 v[250:251], v[48:49], v[210:211], v[250:251]
	v_pk_fma_f32 v[248:249], v[24:25], v[204:205], v[248:249]
	v_pk_fma_f32 v[0:1], v[48:49], v[212:213], v[0:1]
	v_pk_mul_f32 v[202:203], v[246:247], s[40:41]
	v_pk_mul_f32 v[204:205], v[248:249], s[40:41]
	v_exp_f32_e32 v202, v202
	v_exp_f32_e32 v203, v203
	v_exp_f32_e32 v204, v204
	v_exp_f32_e32 v205, v205
	v_pk_mul_f32 v[250:251], v[250:251], v[246:247]
	v_pk_mul_f32 v[0:1], v[0:1], v[248:249]
	v_pk_add_f32 v[202:203], v[202:203], 1.0 op_sel_hi:[1,0]
	v_pk_add_f32 v[204:205], v[204:205], 1.0 op_sel_hi:[1,0]
	v_rcp_f32_e32 v202, v202
	v_rcp_f32_e32 v203, v203
	v_rcp_f32_e32 v204, v204
	v_rcp_f32_e32 v205, v205
	s_nop 0
	v_pk_mul_f32 v[250:251], v[250:251], v[202:203]
	v_pk_mul_f32 v[0:1], v[0:1], v[204:205]
	v_cvt_pk_bf16_f32 v166, v250, v251
	v_cvt_pk_bf16_f32 v170, v0, v1
	v_lshlrev_b32_e32 v202, 16, v167
	v_and_b32_e32 v203, 0xffff0000, v167
	v_lshlrev_b32_e32 v204, 16, v171
	v_and_b32_e32 v205, 0xffff0000, v171
	v_lshlrev_b32_e32 v206, 16, v175
	v_and_b32_e32 v207, 0xffff0000, v175
	v_lshlrev_b32_e32 v208, 16, v179
	v_and_b32_e32 v209, 0xffff0000, v179
	v_lshlrev_b32_e32 v210, 16, v183
	v_and_b32_e32 v211, 0xffff0000, v183
	v_lshlrev_b32_e32 v212, 16, v187
	v_and_b32_e32 v213, 0xffff0000, v187
	v_lshlrev_b32_e32 v214, 16, v191
	v_and_b32_e32 v215, 0xffff0000, v191
	v_lshlrev_b32_e32 v216, 16, v195
	v_and_b32_e32 v217, 0xffff0000, v195
	v_pk_fma_f32 v[246:247], v[42:43], v[206:207], v[10:11]
	v_pk_fma_f32 v[250:251], v[66:67], v[214:215], v[18:19]
	v_pk_fma_f32 v[248:249], v[42:43], v[208:209], v[10:11]
	v_pk_fma_f32 v[0:1], v[66:67], v[216:217], v[18:19]
	v_pk_fma_f32 v[246:247], v[34:35], v[204:205], v[246:247]
	v_pk_fma_f32 v[250:251], v[58:59], v[212:213], v[250:251]
	v_pk_fma_f32 v[248:249], v[34:35], v[206:207], v[248:249]
	v_pk_fma_f32 v[0:1], v[58:59], v[214:215], v[0:1]
	v_pk_fma_f32 v[246:247], v[26:27], v[202:203], v[246:247]
	v_pk_fma_f32 v[250:251], v[50:51], v[210:211], v[250:251]
	v_pk_fma_f32 v[248:249], v[26:27], v[204:205], v[248:249]
	v_pk_fma_f32 v[0:1], v[50:51], v[212:213], v[0:1]
	v_pk_mul_f32 v[202:203], v[246:247], s[40:41]
	v_pk_mul_f32 v[204:205], v[248:249], s[40:41]
	v_exp_f32_e32 v202, v202
	v_exp_f32_e32 v203, v203
	v_exp_f32_e32 v204, v204
	v_exp_f32_e32 v205, v205
	v_pk_mul_f32 v[250:251], v[250:251], v[246:247]
	v_pk_mul_f32 v[0:1], v[0:1], v[248:249]
	v_pk_add_f32 v[202:203], v[202:203], 1.0 op_sel_hi:[1,0]
	v_pk_add_f32 v[204:205], v[204:205], 1.0 op_sel_hi:[1,0]
	v_rcp_f32_e32 v202, v202
	v_rcp_f32_e32 v203, v203
	v_rcp_f32_e32 v204, v204
	v_rcp_f32_e32 v205, v205
	s_nop 0
	v_pk_mul_f32 v[250:251], v[250:251], v[202:203]
	v_pk_mul_f32 v[0:1], v[0:1], v[204:205]
	v_cvt_pk_bf16_f32 v167, v250, v251
	v_cvt_pk_bf16_f32 v171, v0, v1
	s_add_i32 s38, s42, 3
	s_mul_i32 s39, s38, 0x58000
	s_add_u32 s38, s82, s39
	s_addc_u32 s39, s83, 0
	global_store_dwordx4 v236, v[164:167], s[38:39]
	global_store_dwordx4 v237, v[168:171], s[38:39]
	s_branch .LBB0_29

.LBB0_656:
	s_or_b64 exec, exec, s[30:31]
	v_readlane_b32 s0, v254, 59
	v_readlane_b32 s1, v254, 60
	s_nop 3
	s_load_dword s2, s[0:1], 0x0
	s_waitcnt lgkmcnt(0)
	s_cmpk_lg_u32 s2, 0x100
	s_cbranch_scc1 .Lrow0_generic
	v_readlane_b32 s0, v254, 58
	v_readfirstlane_b32 s1, v197
	v_readlane_b32 s4, v254, 42
	v_readlane_b32 s5, v254, 43
	v_readlane_b32 s6, v254, 44
	v_readlane_b32 s7, v254, 45
	v_readlane_b32 s8, v254, 46
	v_readlane_b32 s9, v254, 47
	v_and_b32_e32 v164, 63, v197
	v_lshlrev_b32_e32 v165, 3, v164
	v_lshlrev_b32_e32 v164, 4, v164
	s_lshr_b32 s1, s1, 6
	s_lshl_b32 s0, s0, 3
	s_add_i32 s20, s0, s1
	s_lshl_b32 s0, s20, 12
	s_add_u32 s10, s4, s0
	s_addc_u32 s11, s5, 0
	s_lshl_b32 s0, s20, 11
	s_add_u32 s12, s90, s0
	s_addc_u32 s13, s91, 0
	global_load_dwordx4 v[132:135], v164, s[8:9] offset:0
	global_load_dwordx4 v[136:139], v164, s[8:9] offset:1024
	global_load_dwordx4 v[140:143], v164, s[8:9] offset:2048
	global_load_dwordx4 v[144:147], v164, s[8:9] offset:3072
	s_mov_b64 s[22:23], s[10:11]
	global_load_dwordx4 v[4:7], v164, s[22:23] offset:0 nt
	global_load_dwordx4 v[8:11], v164, s[22:23] offset:1024 nt
	global_load_dwordx4 v[12:15], v164, s[22:23] offset:2048 nt
	global_load_dwordx4 v[16:19], v164, s[22:23] offset:3072 nt
	s_add_u32 s22, s10, 0x800000
	s_addc_u32 s23, s11, 0
	global_load_dwordx4 v[20:23], v164, s[22:23] offset:0 nt
	global_load_dwordx4 v[24:27], v164, s[22:23] offset:1024 nt
	global_load_dwordx4 v[28:31], v164, s[22:23] offset:2048 nt
	global_load_dwordx4 v[32:35], v164, s[22:23] offset:3072 nt
	s_add_u32 s22, s10, 0x1000000
	s_addc_u32 s23, s11, 0
	global_load_dwordx4 v[36:39], v164, s[22:23] offset:0 nt
	global_load_dwordx4 v[40:43], v164, s[22:23] offset:1024 nt
	global_load_dwordx4 v[44:47], v164, s[22:23] offset:2048 nt
	global_load_dwordx4 v[48:51], v164, s[22:23] offset:3072 nt
	s_add_u32 s22, s10, 0x1800000
	s_addc_u32 s23, s11, 0
	global_load_dwordx4 v[52:55], v164, s[22:23] offset:0 nt
	global_load_dwordx4 v[56:59], v164, s[22:23] offset:1024 nt
	global_load_dwordx4 v[60:63], v164, s[22:23] offset:2048 nt
	global_load_dwordx4 v[64:67], v164, s[22:23] offset:3072 nt
	s_add_u32 s22, s10, 0x2000000
	s_addc_u32 s23, s11, 0
	global_load_dwordx4 v[68:71], v164, s[22:23] offset:0 nt
	global_load_dwordx4 v[72:75], v164, s[22:23] offset:1024 nt
	global_load_dwordx4 v[76:79], v164, s[22:23] offset:2048 nt
	global_load_dwordx4 v[80:83], v164, s[22:23] offset:3072 nt
	s_add_u32 s22, s10, 0x2800000
	s_addc_u32 s23, s11, 0
	global_load_dwordx4 v[84:87], v164, s[22:23] offset:0 nt
	global_load_dwordx4 v[88:91], v164, s[22:23] offset:1024 nt
	global_load_dwordx4 v[92:95], v164, s[22:23] offset:2048 nt
	global_load_dwordx4 v[96:99], v164, s[22:23] offset:3072 nt
	s_add_u32 s22, s10, 0x3000000
	s_addc_u32 s23, s11, 0
	global_load_dwordx4 v[100:103], v164, s[22:23] offset:0 nt
	global_load_dwordx4 v[104:107], v164, s[22:23] offset:1024 nt
	global_load_dwordx4 v[108:111], v164, s[22:23] offset:2048 nt
	global_load_dwordx4 v[112:115], v164, s[22:23] offset:3072 nt
	s_add_u32 s22, s10, 0x3800000
	s_addc_u32 s23, s11, 0
	global_load_dwordx4 v[116:119], v164, s[22:23] offset:0 nt
	global_load_dwordx4 v[120:123], v164, s[22:23] offset:1024 nt
	global_load_dwordx4 v[124:127], v164, s[22:23] offset:2048 nt
	global_load_dwordx4 v[128:131], v164, s[22:23] offset:3072 nt
	s_waitcnt vmcnt(28)
	v_pk_mul_f32 v[148:149], v[4:5], v[4:5]
	v_pk_fma_f32 v[148:149], v[6:7], v[6:7], v[148:149]
	v_pk_fma_f32 v[148:149], v[8:9], v[8:9], v[148:149]
	v_pk_fma_f32 v[148:149], v[10:11], v[10:11], v[148:149]
	v_pk_fma_f32 v[148:149], v[12:13], v[12:13], v[148:149]
	v_pk_fma_f32 v[148:149], v[14:15], v[14:15], v[148:149]
	v_pk_fma_f32 v[148:149], v[16:17], v[16:17], v[148:149]
	v_pk_fma_f32 v[148:149], v[18:19], v[18:19], v[148:149]
	s_waitcnt vmcnt(24)
	v_pk_mul_f32 v[150:151], v[20:21], v[20:21]
	v_pk_fma_f32 v[150:151], v[22:23], v[22:23], v[150:151]
	v_pk_fma_f32 v[150:151], v[24:25], v[24:25], v[150:151]
	v_pk_fma_f32 v[150:151], v[26:27], v[26:27], v[150:151]
	v_pk_fma_f32 v[150:151], v[28:29], v[28:29], v[150:151]
	v_pk_fma_f32 v[150:151], v[30:31], v[30:31], v[150:151]
	v_pk_fma_f32 v[150:151], v[32:33], v[32:33], v[150:151]
	v_pk_fma_f32 v[150:151], v[34:35], v[34:35], v[150:151]
	s_waitcnt vmcnt(20)
	v_pk_mul_f32 v[152:153], v[36:37], v[36:37]
	v_pk_fma_f32 v[152:153], v[38:39], v[38:39], v[152:153]
	v_pk_fma_f32 v[152:153], v[40:41], v[40:41], v[152:153]
	v_pk_fma_f32 v[152:153], v[42:43], v[42:43], v[152:153]
	v_pk_fma_f32 v[152:153], v[44:45], v[44:45], v[152:153]
	v_pk_fma_f32 v[152:153], v[46:47], v[46:47], v[152:153]
	v_pk_fma_f32 v[152:153], v[48:49], v[48:49], v[152:153]
	v_pk_fma_f32 v[152:153], v[50:51], v[50:51], v[152:153]
	s_waitcnt vmcnt(16)
	v_pk_mul_f32 v[154:155], v[52:53], v[52:53]
	v_pk_fma_f32 v[154:155], v[54:55], v[54:55], v[154:155]
	v_pk_fma_f32 v[154:155], v[56:57], v[56:57], v[154:155]
	v_pk_fma_f32 v[154:155], v[58:59], v[58:59], v[154:155]
	v_pk_fma_f32 v[154:155], v[60:61], v[60:61], v[154:155]
	v_pk_fma_f32 v[154:155], v[62:63], v[62:63], v[154:155]
	v_pk_fma_f32 v[154:155], v[64:65], v[64:65], v[154:155]
	v_pk_fma_f32 v[154:155], v[66:67], v[66:67], v[154:155]
	v_add_f32_e32 v148, v148, v149
	v_add_f32_e32 v150, v150, v151
	v_add_f32_e32 v152, v152, v153
	v_add_f32_e32 v154, v154, v155
	s_nop 0
	v_add_f32_dpp v148, v148, v148 quad_perm:[1,0,3,2] row_mask:0xf bank_mask:0xf
	v_add_f32_dpp v150, v150, v150 quad_perm:[1,0,3,2] row_mask:0xf bank_mask:0xf
	v_add_f32_dpp v152, v152, v152 quad_perm:[1,0,3,2] row_mask:0xf bank_mask:0xf
	v_add_f32_dpp v154, v154, v154 quad_perm:[1,0,3,2] row_mask:0xf bank_mask:0xf
	s_nop 0
	v_add_f32_dpp v148, v148, v148 quad_perm:[2,3,0,1] row_mask:0xf bank_mask:0xf
	v_add_f32_dpp v150, v150, v150 quad_perm:[2,3,0,1] row_mask:0xf bank_mask:0xf
	v_add_f32_dpp v152, v152, v152 quad_perm:[2,3,0,1] row_mask:0xf bank_mask:0xf
	v_add_f32_dpp v154, v154, v154 quad_perm:[2,3,0,1] row_mask:0xf bank_mask:0xf
	s_nop 0
	v_add_f32_dpp v148, v148, v148 row_half_mirror row_mask:0xf bank_mask:0xf
	v_add_f32_dpp v150, v150, v150 row_half_mirror row_mask:0xf bank_mask:0xf
	v_add_f32_dpp v152, v152, v152 row_half_mirror row_mask:0xf bank_mask:0xf
	v_add_f32_dpp v154, v154, v154 row_half_mirror row_mask:0xf bank_mask:0xf
	s_nop 0
	v_add_f32_dpp v148, v148, v148 row_mirror row_mask:0xf bank_mask:0xf
	v_add_f32_dpp v150, v150, v150 row_mirror row_mask:0xf bank_mask:0xf
	v_add_f32_dpp v152, v152, v152 row_mirror row_mask:0xf bank_mask:0xf
	v_add_f32_dpp v154, v154, v154 row_mirror row_mask:0xf bank_mask:0xf
	s_nop 0
	v_add_f32_dpp v148, v148, v148 row_bcast:15 row_mask:0xa bank_mask:0xf
	v_add_f32_dpp v150, v150, v150 row_bcast:15 row_mask:0xa bank_mask:0xf
	v_add_f32_dpp v152, v152, v152 row_bcast:15 row_mask:0xa bank_mask:0xf
	v_add_f32_dpp v154, v154, v154 row_bcast:15 row_mask:0xa bank_mask:0xf
	s_nop 0
	v_add_f32_dpp v148, v148, v148 row_bcast:31 row_mask:0xc bank_mask:0xf
	v_add_f32_dpp v150, v150, v150 row_bcast:31 row_mask:0xc bank_mask:0xf
	v_add_f32_dpp v152, v152, v152 row_bcast:31 row_mask:0xc bank_mask:0xf
	v_add_f32_dpp v154, v154, v154 row_bcast:31 row_mask:0xc bank_mask:0xf
	s_nop 1
	v_readlane_b32 s0, v148, 63
	v_readlane_b32 s1, v150, 63
	v_readlane_b32 s2, v152, 63
	v_readlane_b32 s3, v154, 63
	s_nop 1
	v_mov_b32_e32 v156, s0
	v_mov_b32_e32 v158, s1
	v_mov_b32_e32 v160, s2
	v_mov_b32_e32 v162, s3
	v_fmamk_f32 v156, v156, 0x3a800000, v196
	v_fmamk_f32 v158, v158, 0x3a800000, v196
	v_fmamk_f32 v160, v160, 0x3a800000, v196
	v_fmamk_f32 v162, v162, 0x3a800000, v196
	v_rsq_f32_e32 v156, v156
	v_rsq_f32_e32 v158, v158
	v_rsq_f32_e32 v160, v160
	v_rsq_f32_e32 v162, v162
	s_nop 0
	v_pk_mul_f32 v[4:5], v[4:5], v[156:157] op_sel_hi:[1,0]
	v_pk_mul_f32 v[6:7], v[6:7], v[156:157] op_sel_hi:[1,0]
	v_pk_mul_f32 v[8:9], v[8:9], v[156:157] op_sel_hi:[1,0]
	v_pk_mul_f32 v[10:11], v[10:11], v[156:157] op_sel_hi:[1,0]
	v_pk_mul_f32 v[12:13], v[12:13], v[156:157] op_sel_hi:[1,0]
	v_pk_mul_f32 v[14:15], v[14:15], v[156:157] op_sel_hi:[1,0]
	v_pk_mul_f32 v[16:17], v[16:17], v[156:157] op_sel_hi:[1,0]
	v_pk_mul_f32 v[18:19], v[18:19], v[156:157] op_sel_hi:[1,0]
	v_pk_mul_f32 v[4:5], v[4:5], v[132:133]
	v_pk_mul_f32 v[6:7], v[6:7], v[134:135]
	v_pk_mul_f32 v[8:9], v[8:9], v[136:137]
	v_pk_mul_f32 v[10:11], v[10:11], v[138:139]
	v_pk_mul_f32 v[12:13], v[12:13], v[140:141]
	v_pk_mul_f32 v[14:15], v[14:15], v[142:143]
	v_pk_mul_f32 v[16:17], v[16:17], v[144:145]
	v_pk_mul_f32 v[18:19], v[18:19], v[146:147]
	v_cvt_pk_bf16_f32 v4, v4, v5
	v_cvt_pk_bf16_f32 v5, v6, v7
	v_cvt_pk_bf16_f32 v6, v8, v9
	v_cvt_pk_bf16_f32 v7, v10, v11
	v_cvt_pk_bf16_f32 v8, v12, v13
	v_cvt_pk_bf16_f32 v9, v14, v15
	v_cvt_pk_bf16_f32 v10, v16, v17
	v_cvt_pk_bf16_f32 v11, v18, v19
	s_mov_b64 s[24:25], s[12:13]
	global_store_dwordx2 v165, v[4:5], s[24:25] offset:0
	global_store_dwordx2 v165, v[6:7], s[24:25] offset:512
	global_store_dwordx2 v165, v[8:9], s[24:25] offset:1024
	global_store_dwordx2 v165, v[10:11], s[24:25] offset:1536
	v_pk_mul_f32 v[20:21], v[20:21], v[158:159] op_sel_hi:[1,0]
	v_pk_mul_f32 v[22:23], v[22:23], v[158:159] op_sel_hi:[1,0]
	v_pk_mul_f32 v[24:25], v[24:25], v[158:159] op_sel_hi:[1,0]
	v_pk_mul_f32 v[26:27], v[26:27], v[158:159] op_sel_hi:[1,0]
	v_pk_mul_f32 v[28:29], v[28:29], v[158:159] op_sel_hi:[1,0]
	v_pk_mul_f32 v[30:31], v[30:31], v[158:159] op_sel_hi:[1,0]
	v_pk_mul_f32 v[32:33], v[32:33], v[158:159] op_sel_hi:[1,0]
	v_pk_mul_f32 v[34:35], v[34:35], v[158:159] op_sel_hi:[1,0]
	v_pk_mul_f32 v[20:21], v[20:21], v[132:133]
	v_pk_mul_f32 v[22:23], v[22:23], v[134:135]
	v_pk_mul_f32 v[24:25], v[24:25], v[136:137]
	v_pk_mul_f32 v[26:27], v[26:27], v[138:139]
	v_pk_mul_f32 v[28:29], v[28:29], v[140:141]
	v_pk_mul_f32 v[30:31], v[30:31], v[142:143]
	v_pk_mul_f32 v[32:33], v[32:33], v[144:145]
	v_pk_mul_f32 v[34:35], v[34:35], v[146:147]
	v_cvt_pk_bf16_f32 v20, v20, v21
	v_cvt_pk_bf16_f32 v21, v22, v23
	v_cvt_pk_bf16_f32 v22, v24, v25
	v_cvt_pk_bf16_f32 v23, v26, v27
	v_cvt_pk_bf16_f32 v24, v28, v29
	v_cvt_pk_bf16_f32 v25, v30, v31
	v_cvt_pk_bf16_f32 v26, v32, v33
	v_cvt_pk_bf16_f32 v27, v34, v35
	s_add_u32 s24, s12, 0x400000
	s_addc_u32 s25, s13, 0
	global_store_dwordx2 v165, v[20:21], s[24:25] offset:0
	global_store_dwordx2 v165, v[22:23], s[24:25] offset:512
	global_store_dwordx2 v165, v[24:25], s[24:25] offset:1024
	global_store_dwordx2 v165, v[26:27], s[24:25] offset:1536
	v_pk_mul_f32 v[36:37], v[36:37], v[160:161] op_sel_hi:[1,0]
	v_pk_mul_f32 v[38:39], v[38:39], v[160:161] op_sel_hi:[1,0]
	v_pk_mul_f32 v[40:41], v[40:41], v[160:161] op_sel_hi:[1,0]
	v_pk_mul_f32 v[42:43], v[42:43], v[160:161] op_sel_hi:[1,0]
	v_pk_mul_f32 v[44:45], v[44:45], v[160:161] op_sel_hi:[1,0]
	v_pk_mul_f32 v[46:47], v[46:47], v[160:161] op_sel_hi:[1,0]
	v_pk_mul_f32 v[48:49], v[48:49], v[160:161] op_sel_hi:[1,0]
	v_pk_mul_f32 v[50:51], v[50:51], v[160:161] op_sel_hi:[1,0]
	v_pk_mul_f32 v[36:37], v[36:37], v[132:133]
	v_pk_mul_f32 v[38:39], v[38:39], v[134:135]
	v_pk_mul_f32 v[40:41], v[40:41], v[136:137]
	v_pk_mul_f32 v[42:43], v[42:43], v[138:139]
	v_pk_mul_f32 v[44:45], v[44:45], v[140:141]
	v_pk_mul_f32 v[46:47], v[46:47], v[142:143]
	v_pk_mul_f32 v[48:49], v[48:49], v[144:145]
	v_pk_mul_f32 v[50:51], v[50:51], v[146:147]
	v_cvt_pk_bf16_f32 v36, v36, v37
	v_cvt_pk_bf16_f32 v37, v38, v39
	v_cvt_pk_bf16_f32 v38, v40, v41
	v_cvt_pk_bf16_f32 v39, v42, v43
	v_cvt_pk_bf16_f32 v40, v44, v45
	v_cvt_pk_bf16_f32 v41, v46, v47
	v_cvt_pk_bf16_f32 v42, v48, v49
	v_cvt_pk_bf16_f32 v43, v50, v51
	s_add_u32 s24, s12, 0x800000
	s_addc_u32 s25, s13, 0
	global_store_dwordx2 v165, v[36:37], s[24:25] offset:0
	global_store_dwordx2 v165, v[38:39], s[24:25] offset:512
	global_store_dwordx2 v165, v[40:41], s[24:25] offset:1024
	global_store_dwordx2 v165, v[42:43], s[24:25] offset:1536
	v_pk_mul_f32 v[52:53], v[52:53], v[162:163] op_sel_hi:[1,0]
	v_pk_mul_f32 v[54:55], v[54:55], v[162:163] op_sel_hi:[1,0]
	v_pk_mul_f32 v[56:57], v[56:57], v[162:163] op_sel_hi:[1,0]
	v_pk_mul_f32 v[58:59], v[58:59], v[162:163] op_sel_hi:[1,0]
	v_pk_mul_f32 v[60:61], v[60:61], v[162:163] op_sel_hi:[1,0]
	v_pk_mul_f32 v[62:63], v[62:63], v[162:163] op_sel_hi:[1,0]
	v_pk_mul_f32 v[64:65], v[64:65], v[162:163] op_sel_hi:[1,0]
	v_pk_mul_f32 v[66:67], v[66:67], v[162:163] op_sel_hi:[1,0]
	v_pk_mul_f32 v[52:53], v[52:53], v[132:133]
	v_pk_mul_f32 v[54:55], v[54:55], v[134:135]
	v_pk_mul_f32 v[56:57], v[56:57], v[136:137]
	v_pk_mul_f32 v[58:59], v[58:59], v[138:139]
	v_pk_mul_f32 v[60:61], v[60:61], v[140:141]
	v_pk_mul_f32 v[62:63], v[62:63], v[142:143]
	v_pk_mul_f32 v[64:65], v[64:65], v[144:145]
	v_pk_mul_f32 v[66:67], v[66:67], v[146:147]
	v_cvt_pk_bf16_f32 v52, v52, v53
	v_cvt_pk_bf16_f32 v53, v54, v55
	v_cvt_pk_bf16_f32 v54, v56, v57
	v_cvt_pk_bf16_f32 v55, v58, v59
	v_cvt_pk_bf16_f32 v56, v60, v61
	v_cvt_pk_bf16_f32 v57, v62, v63
	v_cvt_pk_bf16_f32 v58, v64, v65
	v_cvt_pk_bf16_f32 v59, v66, v67
	s_add_u32 s24, s12, 0xc00000
	s_addc_u32 s25, s13, 0
	global_store_dwordx2 v165, v[52:53], s[24:25] offset:0
	global_store_dwordx2 v165, v[54:55], s[24:25] offset:512
	global_store_dwordx2 v165, v[56:57], s[24:25] offset:1024
	global_store_dwordx2 v165, v[58:59], s[24:25] offset:1536
	s_add_u32 s22, s10, 0x4000000
	s_addc_u32 s23, s11, 0
	global_load_dwordx4 v[4:7], v164, s[22:23] offset:0 nt
	global_load_dwordx4 v[8:11], v164, s[22:23] offset:1024 nt
	global_load_dwordx4 v[12:15], v164, s[22:23] offset:2048 nt
	global_load_dwordx4 v[16:19], v164, s[22:23] offset:3072 nt
	s_add_u32 s22, s10, 0x4800000
	s_addc_u32 s23, s11, 0
	global_load_dwordx4 v[20:23], v164, s[22:23] offset:0 nt
	global_load_dwordx4 v[24:27], v164, s[22:23] offset:1024 nt
	global_load_dwordx4 v[28:31], v164, s[22:23] offset:2048 nt
	global_load_dwordx4 v[32:35], v164, s[22:23] offset:3072 nt
	s_add_u32 s22, s10, 0x5000000
	s_addc_u32 s23, s11, 0
	global_load_dwordx4 v[36:39], v164, s[22:23] offset:0 nt
	global_load_dwordx4 v[40:43], v164, s[22:23] offset:1024 nt
	global_load_dwordx4 v[44:47], v164, s[22:23] offset:2048 nt
	global_load_dwordx4 v[48:51], v164, s[22:23] offset:3072 nt
	s_add_u32 s22, s10, 0x5800000
	s_addc_u32 s23, s11, 0
	global_load_dwordx4 v[52:55], v164, s[22:23] offset:0 nt
	global_load_dwordx4 v[56:59], v164, s[22:23] offset:1024 nt
	global_load_dwordx4 v[60:63], v164, s[22:23] offset:2048 nt
	global_load_dwordx4 v[64:67], v164, s[22:23] offset:3072 nt
	s_waitcnt vmcnt(44)
	v_pk_mul_f32 v[148:149], v[68:69], v[68:69]
	v_pk_fma_f32 v[148:149], v[70:71], v[70:71], v[148:149]
	v_pk_fma_f32 v[148:149], v[72:73], v[72:73], v[148:149]
	v_pk_fma_f32 v[148:149], v[74:75], v[74:75], v[148:149]
	v_pk_fma_f32 v[148:149], v[76:77], v[76:77], v[148:149]
	v_pk_fma_f32 v[148:149], v[78:79], v[78:79], v[148:149]
	v_pk_fma_f32 v[148:149], v[80:81], v[80:81], v[148:149]
	v_pk_fma_f32 v[148:149], v[82:83], v[82:83], v[148:149]
	s_waitcnt vmcnt(40)
	v_pk_mul_f32 v[150:151], v[84:85], v[84:85]
	v_pk_fma_f32 v[150:151], v[86:87], v[86:87], v[150:151]
	v_pk_fma_f32 v[150:151], v[88:89], v[88:89], v[150:151]
	v_pk_fma_f32 v[150:151], v[90:91], v[90:91], v[150:151]
	v_pk_fma_f32 v[150:151], v[92:93], v[92:93], v[150:151]
	v_pk_fma_f32 v[150:151], v[94:95], v[94:95], v[150:151]
	v_pk_fma_f32 v[150:151], v[96:97], v[96:97], v[150:151]
	v_pk_fma_f32 v[150:151], v[98:99], v[98:99], v[150:151]
	s_waitcnt vmcnt(36)
	v_pk_mul_f32 v[152:153], v[100:101], v[100:101]
	v_pk_fma_f32 v[152:153], v[102:103], v[102:103], v[152:153]
	v_pk_fma_f32 v[152:153], v[104:105], v[104:105], v[152:153]
	v_pk_fma_f32 v[152:153], v[106:107], v[106:107], v[152:153]
	v_pk_fma_f32 v[152:153], v[108:109], v[108:109], v[152:153]
	v_pk_fma_f32 v[152:153], v[110:111], v[110:111], v[152:153]
	v_pk_fma_f32 v[152:153], v[112:113], v[112:113], v[152:153]
	v_pk_fma_f32 v[152:153], v[114:115], v[114:115], v[152:153]
	s_waitcnt vmcnt(32)
	v_pk_mul_f32 v[154:155], v[116:117], v[116:117]
	v_pk_fma_f32 v[154:155], v[118:119], v[118:119], v[154:155]
	v_pk_fma_f32 v[154:155], v[120:121], v[120:121], v[154:155]
	v_pk_fma_f32 v[154:155], v[122:123], v[122:123], v[154:155]
	v_pk_fma_f32 v[154:155], v[124:125], v[124:125], v[154:155]
	v_pk_fma_f32 v[154:155], v[126:127], v[126:127], v[154:155]
	v_pk_fma_f32 v[154:155], v[128:129], v[128:129], v[154:155]
	v_pk_fma_f32 v[154:155], v[130:131], v[130:131], v[154:155]
	v_add_f32_e32 v148, v148, v149
	v_add_f32_e32 v150, v150, v151
	v_add_f32_e32 v152, v152, v153
	v_add_f32_e32 v154, v154, v155
	s_nop 0
	v_add_f32_dpp v148, v148, v148 quad_perm:[1,0,3,2] row_mask:0xf bank_mask:0xf
	v_add_f32_dpp v150, v150, v150 quad_perm:[1,0,3,2] row_mask:0xf bank_mask:0xf
	v_add_f32_dpp v152, v152, v152 quad_perm:[1,0,3,2] row_mask:0xf bank_mask:0xf
	v_add_f32_dpp v154, v154, v154 quad_perm:[1,0,3,2] row_mask:0xf bank_mask:0xf
	s_nop 0
	v_add_f32_dpp v148, v148, v148 quad_perm:[2,3,0,1] row_mask:0xf bank_mask:0xf
	v_add_f32_dpp v150, v150, v150 quad_perm:[2,3,0,1] row_mask:0xf bank_mask:0xf
	v_add_f32_dpp v152, v152, v152 quad_perm:[2,3,0,1] row_mask:0xf bank_mask:0xf
	v_add_f32_dpp v154, v154, v154 quad_perm:[2,3,0,1] row_mask:0xf bank_mask:0xf
	s_nop 0
	v_add_f32_dpp v148, v148, v148 row_half_mirror row_mask:0xf bank_mask:0xf
	v_add_f32_dpp v150, v150, v150 row_half_mirror row_mask:0xf bank_mask:0xf
	v_add_f32_dpp v152, v152, v152 row_half_mirror row_mask:0xf bank_mask:0xf
	v_add_f32_dpp v154, v154, v154 row_half_mirror row_mask:0xf bank_mask:0xf
	s_nop 0
	v_add_f32_dpp v148, v148, v148 row_mirror row_mask:0xf bank_mask:0xf
	v_add_f32_dpp v150, v150, v150 row_mirror row_mask:0xf bank_mask:0xf
	v_add_f32_dpp v152, v152, v152 row_mirror row_mask:0xf bank_mask:0xf
	v_add_f32_dpp v154, v154, v154 row_mirror row_mask:0xf bank_mask:0xf
	s_nop 0
	v_add_f32_dpp v148, v148, v148 row_bcast:15 row_mask:0xa bank_mask:0xf
	v_add_f32_dpp v150, v150, v150 row_bcast:15 row_mask:0xa bank_mask:0xf
	v_add_f32_dpp v152, v152, v152 row_bcast:15 row_mask:0xa bank_mask:0xf
	v_add_f32_dpp v154, v154, v154 row_bcast:15 row_mask:0xa bank_mask:0xf
	s_nop 0
	v_add_f32_dpp v148, v148, v148 row_bcast:31 row_mask:0xc bank_mask:0xf
	v_add_f32_dpp v150, v150, v150 row_bcast:31 row_mask:0xc bank_mask:0xf
	v_add_f32_dpp v152, v152, v152 row_bcast:31 row_mask:0xc bank_mask:0xf
	v_add_f32_dpp v154, v154, v154 row_bcast:31 row_mask:0xc bank_mask:0xf
	s_nop 1
	v_readlane_b32 s0, v148, 63
	v_readlane_b32 s1, v150, 63
	v_readlane_b32 s2, v152, 63
	v_readlane_b32 s3, v154, 63
	s_nop 1
	v_mov_b32_e32 v156, s0
	v_mov_b32_e32 v158, s1
	v_mov_b32_e32 v160, s2
	v_mov_b32_e32 v162, s3
	v_fmamk_f32 v156, v156, 0x3a800000, v196
	v_fmamk_f32 v158, v158, 0x3a800000, v196
	v_fmamk_f32 v160, v160, 0x3a800000, v196
	v_fmamk_f32 v162, v162, 0x3a800000, v196
	v_rsq_f32_e32 v156, v156
	v_rsq_f32_e32 v158, v158
	v_rsq_f32_e32 v160, v160
	v_rsq_f32_e32 v162, v162
	s_nop 0
	v_pk_mul_f32 v[68:69], v[68:69], v[156:157] op_sel_hi:[1,0]
	v_pk_mul_f32 v[70:71], v[70:71], v[156:157] op_sel_hi:[1,0]
	v_pk_mul_f32 v[72:73], v[72:73], v[156:157] op_sel_hi:[1,0]
	v_pk_mul_f32 v[74:75], v[74:75], v[156:157] op_sel_hi:[1,0]
	v_pk_mul_f32 v[76:77], v[76:77], v[156:157] op_sel_hi:[1,0]
	v_pk_mul_f32 v[78:79], v[78:79], v[156:157] op_sel_hi:[1,0]
	v_pk_mul_f32 v[80:81], v[80:81], v[156:157] op_sel_hi:[1,0]
	v_pk_mul_f32 v[82:83], v[82:83], v[156:157] op_sel_hi:[1,0]
	v_pk_mul_f32 v[68:69], v[68:69], v[132:133]
	v_pk_mul_f32 v[70:71], v[70:71], v[134:135]
	v_pk_mul_f32 v[72:73], v[72:73], v[136:137]
	v_pk_mul_f32 v[74:75], v[74:75], v[138:139]
	v_pk_mul_f32 v[76:77], v[76:77], v[140:141]
	v_pk_mul_f32 v[78:79], v[78:79], v[142:143]
	v_pk_mul_f32 v[80:81], v[80:81], v[144:145]
	v_pk_mul_f32 v[82:83], v[82:83], v[146:147]
	v_cvt_pk_bf16_f32 v68, v68, v69
	v_cvt_pk_bf16_f32 v69, v70, v71
	v_cvt_pk_bf16_f32 v70, v72, v73
	v_cvt_pk_bf16_f32 v71, v74, v75
	v_cvt_pk_bf16_f32 v72, v76, v77
	v_cvt_pk_bf16_f32 v73, v78, v79
	v_cvt_pk_bf16_f32 v74, v80, v81
	v_cvt_pk_bf16_f32 v75, v82, v83
	s_add_u32 s24, s12, 0x1000000
	s_addc_u32 s25, s13, 0
	global_store_dwordx2 v165, v[68:69], s[24:25] offset:0
	global_store_dwordx2 v165, v[70:71], s[24:25] offset:512
	global_store_dwordx2 v165, v[72:73], s[24:25] offset:1024
	global_store_dwordx2 v165, v[74:75], s[24:25] offset:1536
	v_pk_mul_f32 v[84:85], v[84:85], v[158:159] op_sel_hi:[1,0]
	v_pk_mul_f32 v[86:87], v[86:87], v[158:159] op_sel_hi:[1,0]
	v_pk_mul_f32 v[88:89], v[88:89], v[158:159] op_sel_hi:[1,0]
	v_pk_mul_f32 v[90:91], v[90:91], v[158:159] op_sel_hi:[1,0]
	v_pk_mul_f32 v[92:93], v[92:93], v[158:159] op_sel_hi:[1,0]
	v_pk_mul_f32 v[94:95], v[94:95], v[158:159] op_sel_hi:[1,0]
	v_pk_mul_f32 v[96:97], v[96:97], v[158:159] op_sel_hi:[1,0]
	v_pk_mul_f32 v[98:99], v[98:99], v[158:159] op_sel_hi:[1,0]
	v_pk_mul_f32 v[84:85], v[84:85], v[132:133]
	v_pk_mul_f32 v[86:87], v[86:87], v[134:135]
	v_pk_mul_f32 v[88:89], v[88:89], v[136:137]
	v_pk_mul_f32 v[90:91], v[90:91], v[138:139]
	v_pk_mul_f32 v[92:93], v[92:93], v[140:141]
	v_pk_mul_f32 v[94:95], v[94:95], v[142:143]
	v_pk_mul_f32 v[96:97], v[96:97], v[144:145]
	v_pk_mul_f32 v[98:99], v[98:99], v[146:147]
	v_cvt_pk_bf16_f32 v84, v84, v85
	v_cvt_pk_bf16_f32 v85, v86, v87
	v_cvt_pk_bf16_f32 v86, v88, v89
	v_cvt_pk_bf16_f32 v87, v90, v91
	v_cvt_pk_bf16_f32 v88, v92, v93
	v_cvt_pk_bf16_f32 v89, v94, v95
	v_cvt_pk_bf16_f32 v90, v96, v97
	v_cvt_pk_bf16_f32 v91, v98, v99
	s_add_u32 s24, s12, 0x1400000
	s_addc_u32 s25, s13, 0
	global_store_dwordx2 v165, v[84:85], s[24:25] offset:0
	global_store_dwordx2 v165, v[86:87], s[24:25] offset:512
	global_store_dwordx2 v165, v[88:89], s[24:25] offset:1024
	global_store_dwordx2 v165, v[90:91], s[24:25] offset:1536
	v_pk_mul_f32 v[100:101], v[100:101], v[160:161] op_sel_hi:[1,0]
	v_pk_mul_f32 v[102:103], v[102:103], v[160:161] op_sel_hi:[1,0]
	v_pk_mul_f32 v[104:105], v[104:105], v[160:161] op_sel_hi:[1,0]
	v_pk_mul_f32 v[106:107], v[106:107], v[160:161] op_sel_hi:[1,0]
	v_pk_mul_f32 v[108:109], v[108:109], v[160:161] op_sel_hi:[1,0]
	v_pk_mul_f32 v[110:111], v[110:111], v[160:161] op_sel_hi:[1,0]
	v_pk_mul_f32 v[112:113], v[112:113], v[160:161] op_sel_hi:[1,0]
	v_pk_mul_f32 v[114:115], v[114:115], v[160:161] op_sel_hi:[1,0]
	v_pk_mul_f32 v[100:101], v[100:101], v[132:133]
	v_pk_mul_f32 v[102:103], v[102:103], v[134:135]
	v_pk_mul_f32 v[104:105], v[104:105], v[136:137]
	v_pk_mul_f32 v[106:107], v[106:107], v[138:139]
	v_pk_mul_f32 v[108:109], v[108:109], v[140:141]
	v_pk_mul_f32 v[110:111], v[110:111], v[142:143]
	v_pk_mul_f32 v[112:113], v[112:113], v[144:145]
	v_pk_mul_f32 v[114:115], v[114:115], v[146:147]
	v_cvt_pk_bf16_f32 v100, v100, v101
	v_cvt_pk_bf16_f32 v101, v102, v103
	v_cvt_pk_bf16_f32 v102, v104, v105
	v_cvt_pk_bf16_f32 v103, v106, v107
	v_cvt_pk_bf16_f32 v104, v108, v109
	v_cvt_pk_bf16_f32 v105, v110, v111
	v_cvt_pk_bf16_f32 v106, v112, v113
	v_cvt_pk_bf16_f32 v107, v114, v115
	s_add_u32 s24, s12, 0x1800000
	s_addc_u32 s25, s13, 0
	global_store_dwordx2 v165, v[100:101], s[24:25] offset:0
	global_store_dwordx2 v165, v[102:103], s[24:25] offset:512
	global_store_dwordx2 v165, v[104:105], s[24:25] offset:1024
	global_store_dwordx2 v165, v[106:107], s[24:25] offset:1536
	v_pk_mul_f32 v[116:117], v[116:117], v[162:163] op_sel_hi:[1,0]
	v_pk_mul_f32 v[118:119], v[118:119], v[162:163] op_sel_hi:[1,0]
	v_pk_mul_f32 v[120:121], v[120:121], v[162:163] op_sel_hi:[1,0]
	v_pk_mul_f32 v[122:123], v[122:123], v[162:163] op_sel_hi:[1,0]
	v_pk_mul_f32 v[124:125], v[124:125], v[162:163] op_sel_hi:[1,0]
	v_pk_mul_f32 v[126:127], v[126:127], v[162:163] op_sel_hi:[1,0]
	v_pk_mul_f32 v[128:129], v[128:129], v[162:163] op_sel_hi:[1,0]
	v_pk_mul_f32 v[130:131], v[130:131], v[162:163] op_sel_hi:[1,0]
	v_pk_mul_f32 v[116:117], v[116:117], v[132:133]
	v_pk_mul_f32 v[118:119], v[118:119], v[134:135]
	v_pk_mul_f32 v[120:121], v[120:121], v[136:137]
	v_pk_mul_f32 v[122:123], v[122:123], v[138:139]
	v_pk_mul_f32 v[124:125], v[124:125], v[140:141]
	v_pk_mul_f32 v[126:127], v[126:127], v[142:143]
	v_pk_mul_f32 v[128:129], v[128:129], v[144:145]
	v_pk_mul_f32 v[130:131], v[130:131], v[146:147]
	v_cvt_pk_bf16_f32 v116, v116, v117
	v_cvt_pk_bf16_f32 v117, v118, v119
	v_cvt_pk_bf16_f32 v118, v120, v121
	v_cvt_pk_bf16_f32 v119, v122, v123
	v_cvt_pk_bf16_f32 v120, v124, v125
	v_cvt_pk_bf16_f32 v121, v126, v127
	v_cvt_pk_bf16_f32 v122, v128, v129
	v_cvt_pk_bf16_f32 v123, v130, v131
	s_add_u32 s24, s12, 0x1c00000
	s_addc_u32 s25, s13, 0
	global_store_dwordx2 v165, v[116:117], s[24:25] offset:0
	global_store_dwordx2 v165, v[118:119], s[24:25] offset:512
	global_store_dwordx2 v165, v[120:121], s[24:25] offset:1024
	global_store_dwordx2 v165, v[122:123], s[24:25] offset:1536
	s_add_u32 s22, s10, 0x6000000
	s_addc_u32 s23, s11, 0
	global_load_dwordx4 v[68:71], v164, s[22:23] offset:0 nt
	global_load_dwordx4 v[72:75], v164, s[22:23] offset:1024 nt
	global_load_dwordx4 v[76:79], v164, s[22:23] offset:2048 nt
	global_load_dwordx4 v[80:83], v164, s[22:23] offset:3072 nt
	s_add_u32 s22, s10, 0x6800000
	s_addc_u32 s23, s11, 0
	global_load_dwordx4 v[84:87], v164, s[22:23] offset:0 nt
	global_load_dwordx4 v[88:91], v164, s[22:23] offset:1024 nt
	global_load_dwordx4 v[92:95], v164, s[22:23] offset:2048 nt
	global_load_dwordx4 v[96:99], v164, s[22:23] offset:3072 nt
	s_add_u32 s22, s10, 0x7000000
	s_addc_u32 s23, s11, 0
	global_load_dwordx4 v[100:103], v164, s[22:23] offset:0 nt
	global_load_dwordx4 v[104:107], v164, s[22:23] offset:1024 nt
	global_load_dwordx4 v[108:111], v164, s[22:23] offset:2048 nt
	global_load_dwordx4 v[112:115], v164, s[22:23] offset:3072 nt
	s_add_u32 s22, s10, 0x7800000
	s_addc_u32 s23, s11, 0
	global_load_dwordx4 v[116:119], v164, s[22:23] offset:0 nt
	global_load_dwordx4 v[120:123], v164, s[22:23] offset:1024 nt
	global_load_dwordx4 v[124:127], v164, s[22:23] offset:2048 nt
	global_load_dwordx4 v[128:131], v164, s[22:23] offset:3072 nt
	s_waitcnt vmcnt(44)
	v_pk_mul_f32 v[148:149], v[4:5], v[4:5]
	v_pk_fma_f32 v[148:149], v[6:7], v[6:7], v[148:149]
	v_pk_fma_f32 v[148:149], v[8:9], v[8:9], v[148:149]
	v_pk_fma_f32 v[148:149], v[10:11], v[10:11], v[148:149]
	v_pk_fma_f32 v[148:149], v[12:13], v[12:13], v[148:149]
	v_pk_fma_f32 v[148:149], v[14:15], v[14:15], v[148:149]
	v_pk_fma_f32 v[148:149], v[16:17], v[16:17], v[148:149]
	v_pk_fma_f32 v[148:149], v[18:19], v[18:19], v[148:149]
	s_waitcnt vmcnt(40)
	v_pk_mul_f32 v[150:151], v[20:21], v[20:21]
	v_pk_fma_f32 v[150:151], v[22:23], v[22:23], v[150:151]
	v_pk_fma_f32 v[150:151], v[24:25], v[24:25], v[150:151]
	v_pk_fma_f32 v[150:151], v[26:27], v[26:27], v[150:151]
	v_pk_fma_f32 v[150:151], v[28:29], v[28:29], v[150:151]
	v_pk_fma_f32 v[150:151], v[30:31], v[30:31], v[150:151]
	v_pk_fma_f32 v[150:151], v[32:33], v[32:33], v[150:151]
	v_pk_fma_f32 v[150:151], v[34:35], v[34:35], v[150:151]
	s_waitcnt vmcnt(36)
	v_pk_mul_f32 v[152:153], v[36:37], v[36:37]
	v_pk_fma_f32 v[152:153], v[38:39], v[38:39], v[152:153]
	v_pk_fma_f32 v[152:153], v[40:41], v[40:41], v[152:153]
	v_pk_fma_f32 v[152:153], v[42:43], v[42:43], v[152:153]
	v_pk_fma_f32 v[152:153], v[44:45], v[44:45], v[152:153]
	v_pk_fma_f32 v[152:153], v[46:47], v[46:47], v[152:153]
	v_pk_fma_f32 v[152:153], v[48:49], v[48:49], v[152:153]
	v_pk_fma_f32 v[152:153], v[50:51], v[50:51], v[152:153]
	s_waitcnt vmcnt(32)
	v_pk_mul_f32 v[154:155], v[52:53], v[52:53]
	v_pk_fma_f32 v[154:155], v[54:55], v[54:55], v[154:155]
	v_pk_fma_f32 v[154:155], v[56:57], v[56:57], v[154:155]
	v_pk_fma_f32 v[154:155], v[58:59], v[58:59], v[154:155]
	v_pk_fma_f32 v[154:155], v[60:61], v[60:61], v[154:155]
	v_pk_fma_f32 v[154:155], v[62:63], v[62:63], v[154:155]
	v_pk_fma_f32 v[154:155], v[64:65], v[64:65], v[154:155]
	v_pk_fma_f32 v[154:155], v[66:67], v[66:67], v[154:155]
	v_add_f32_e32 v148, v148, v149
	v_add_f32_e32 v150, v150, v151
	v_add_f32_e32 v152, v152, v153
	v_add_f32_e32 v154, v154, v155
	s_nop 0
	v_add_f32_dpp v148, v148, v148 quad_perm:[1,0,3,2] row_mask:0xf bank_mask:0xf
	v_add_f32_dpp v150, v150, v150 quad_perm:[1,0,3,2] row_mask:0xf bank_mask:0xf
	v_add_f32_dpp v152, v152, v152 quad_perm:[1,0,3,2] row_mask:0xf bank_mask:0xf
	v_add_f32_dpp v154, v154, v154 quad_perm:[1,0,3,2] row_mask:0xf bank_mask:0xf
	s_nop 0
	v_add_f32_dpp v148, v148, v148 quad_perm:[2,3,0,1] row_mask:0xf bank_mask:0xf
	v_add_f32_dpp v150, v150, v150 quad_perm:[2,3,0,1] row_mask:0xf bank_mask:0xf
	v_add_f32_dpp v152, v152, v152 quad_perm:[2,3,0,1] row_mask:0xf bank_mask:0xf
	v_add_f32_dpp v154, v154, v154 quad_perm:[2,3,0,1] row_mask:0xf bank_mask:0xf
	s_nop 0
	v_add_f32_dpp v148, v148, v148 row_half_mirror row_mask:0xf bank_mask:0xf
	v_add_f32_dpp v150, v150, v150 row_half_mirror row_mask:0xf bank_mask:0xf
	v_add_f32_dpp v152, v152, v152 row_half_mirror row_mask:0xf bank_mask:0xf
	v_add_f32_dpp v154, v154, v154 row_half_mirror row_mask:0xf bank_mask:0xf
	s_nop 0
	v_add_f32_dpp v148, v148, v148 row_mirror row_mask:0xf bank_mask:0xf
	v_add_f32_dpp v150, v150, v150 row_mirror row_mask:0xf bank_mask:0xf
	v_add_f32_dpp v152, v152, v152 row_mirror row_mask:0xf bank_mask:0xf
	v_add_f32_dpp v154, v154, v154 row_mirror row_mask:0xf bank_mask:0xf
	s_nop 0
	v_add_f32_dpp v148, v148, v148 row_bcast:15 row_mask:0xa bank_mask:0xf
	v_add_f32_dpp v150, v150, v150 row_bcast:15 row_mask:0xa bank_mask:0xf
	v_add_f32_dpp v152, v152, v152 row_bcast:15 row_mask:0xa bank_mask:0xf
	v_add_f32_dpp v154, v154, v154 row_bcast:15 row_mask:0xa bank_mask:0xf
	s_nop 0
	v_add_f32_dpp v148, v148, v148 row_bcast:31 row_mask:0xc bank_mask:0xf
	v_add_f32_dpp v150, v150, v150 row_bcast:31 row_mask:0xc bank_mask:0xf
	v_add_f32_dpp v152, v152, v152 row_bcast:31 row_mask:0xc bank_mask:0xf
	v_add_f32_dpp v154, v154, v154 row_bcast:31 row_mask:0xc bank_mask:0xf
	s_nop 1
	v_readlane_b32 s0, v148, 63
	v_readlane_b32 s1, v150, 63
	v_readlane_b32 s2, v152, 63
	v_readlane_b32 s3, v154, 63
	s_nop 1
	v_mov_b32_e32 v156, s0
	v_mov_b32_e32 v158, s1
	v_mov_b32_e32 v160, s2
	v_mov_b32_e32 v162, s3
	v_fmamk_f32 v156, v156, 0x3a800000, v196
	v_fmamk_f32 v158, v158, 0x3a800000, v196
	v_fmamk_f32 v160, v160, 0x3a800000, v196
	v_fmamk_f32 v162, v162, 0x3a800000, v196
	v_rsq_f32_e32 v156, v156
	v_rsq_f32_e32 v158, v158
	v_rsq_f32_e32 v160, v160
	v_rsq_f32_e32 v162, v162
	s_nop 0
	v_pk_mul_f32 v[4:5], v[4:5], v[156:157] op_sel_hi:[1,0]
	v_pk_mul_f32 v[6:7], v[6:7], v[156:157] op_sel_hi:[1,0]
	v_pk_mul_f32 v[8:9], v[8:9], v[156:157] op_sel_hi:[1,0]
	v_pk_mul_f32 v[10:11], v[10:11], v[156:157] op_sel_hi:[1,0]
	v_pk_mul_f32 v[12:13], v[12:13], v[156:157] op_sel_hi:[1,0]
	v_pk_mul_f32 v[14:15], v[14:15], v[156:157] op_sel_hi:[1,0]
	v_pk_mul_f32 v[16:17], v[16:17], v[156:157] op_sel_hi:[1,0]
	v_pk_mul_f32 v[18:19], v[18:19], v[156:157] op_sel_hi:[1,0]
	v_pk_mul_f32 v[4:5], v[4:5], v[132:133]
	v_pk_mul_f32 v[6:7], v[6:7], v[134:135]
	v_pk_mul_f32 v[8:9], v[8:9], v[136:137]
	v_pk_mul_f32 v[10:11], v[10:11], v[138:139]
	v_pk_mul_f32 v[12:13], v[12:13], v[140:141]
	v_pk_mul_f32 v[14:15], v[14:15], v[142:143]
	v_pk_mul_f32 v[16:17], v[16:17], v[144:145]
	v_pk_mul_f32 v[18:19], v[18:19], v[146:147]
	v_cvt_pk_bf16_f32 v4, v4, v5
	v_cvt_pk_bf16_f32 v5, v6, v7
	v_cvt_pk_bf16_f32 v6, v8, v9
	v_cvt_pk_bf16_f32 v7, v10, v11
	v_cvt_pk_bf16_f32 v8, v12, v13
	v_cvt_pk_bf16_f32 v9, v14, v15
	v_cvt_pk_bf16_f32 v10, v16, v17
	v_cvt_pk_bf16_f32 v11, v18, v19
	s_add_u32 s24, s12, 0x2000000
	s_addc_u32 s25, s13, 0
	global_store_dwordx2 v165, v[4:5], s[24:25] offset:0
	global_store_dwordx2 v165, v[6:7], s[24:25] offset:512
	global_store_dwordx2 v165, v[8:9], s[24:25] offset:1024
	global_store_dwordx2 v165, v[10:11], s[24:25] offset:1536
	v_pk_mul_f32 v[20:21], v[20:21], v[158:159] op_sel_hi:[1,0]
	v_pk_mul_f32 v[22:23], v[22:23], v[158:159] op_sel_hi:[1,0]
	v_pk_mul_f32 v[24:25], v[24:25], v[158:159] op_sel_hi:[1,0]
	v_pk_mul_f32 v[26:27], v[26:27], v[158:159] op_sel_hi:[1,0]
	v_pk_mul_f32 v[28:29], v[28:29], v[158:159] op_sel_hi:[1,0]
	v_pk_mul_f32 v[30:31], v[30:31], v[158:159] op_sel_hi:[1,0]
	v_pk_mul_f32 v[32:33], v[32:33], v[158:159] op_sel_hi:[1,0]
	v_pk_mul_f32 v[34:35], v[34:35], v[158:159] op_sel_hi:[1,0]
	v_pk_mul_f32 v[20:21], v[20:21], v[132:133]
	v_pk_mul_f32 v[22:23], v[22:23], v[134:135]
	v_pk_mul_f32 v[24:25], v[24:25], v[136:137]
	v_pk_mul_f32 v[26:27], v[26:27], v[138:139]
	v_pk_mul_f32 v[28:29], v[28:29], v[140:141]
	v_pk_mul_f32 v[30:31], v[30:31], v[142:143]
	v_pk_mul_f32 v[32:33], v[32:33], v[144:145]
	v_pk_mul_f32 v[34:35], v[34:35], v[146:147]
	v_cvt_pk_bf16_f32 v20, v20, v21
	v_cvt_pk_bf16_f32 v21, v22, v23
	v_cvt_pk_bf16_f32 v22, v24, v25
	v_cvt_pk_bf16_f32 v23, v26, v27
	v_cvt_pk_bf16_f32 v24, v28, v29
	v_cvt_pk_bf16_f32 v25, v30, v31
	v_cvt_pk_bf16_f32 v26, v32, v33
	v_cvt_pk_bf16_f32 v27, v34, v35
	s_add_u32 s24, s12, 0x2400000
	s_addc_u32 s25, s13, 0
	global_store_dwordx2 v165, v[20:21], s[24:25] offset:0
	global_store_dwordx2 v165, v[22:23], s[24:25] offset:512
	global_store_dwordx2 v165, v[24:25], s[24:25] offset:1024
	global_store_dwordx2 v165, v[26:27], s[24:25] offset:1536
	v_pk_mul_f32 v[36:37], v[36:37], v[160:161] op_sel_hi:[1,0]
	v_pk_mul_f32 v[38:39], v[38:39], v[160:161] op_sel_hi:[1,0]
	v_pk_mul_f32 v[40:41], v[40:41], v[160:161] op_sel_hi:[1,0]
	v_pk_mul_f32 v[42:43], v[42:43], v[160:161] op_sel_hi:[1,0]
	v_pk_mul_f32 v[44:45], v[44:45], v[160:161] op_sel_hi:[1,0]
	v_pk_mul_f32 v[46:47], v[46:47], v[160:161] op_sel_hi:[1,0]
	v_pk_mul_f32 v[48:49], v[48:49], v[160:161] op_sel_hi:[1,0]
	v_pk_mul_f32 v[50:51], v[50:51], v[160:161] op_sel_hi:[1,0]
	v_pk_mul_f32 v[36:37], v[36:37], v[132:133]
	v_pk_mul_f32 v[38:39], v[38:39], v[134:135]
	v_pk_mul_f32 v[40:41], v[40:41], v[136:137]
	v_pk_mul_f32 v[42:43], v[42:43], v[138:139]
	v_pk_mul_f32 v[44:45], v[44:45], v[140:141]
	v_pk_mul_f32 v[46:47], v[46:47], v[142:143]
	v_pk_mul_f32 v[48:49], v[48:49], v[144:145]
	v_pk_mul_f32 v[50:51], v[50:51], v[146:147]
	v_cvt_pk_bf16_f32 v36, v36, v37
	v_cvt_pk_bf16_f32 v37, v38, v39
	v_cvt_pk_bf16_f32 v38, v40, v41
	v_cvt_pk_bf16_f32 v39, v42, v43
	v_cvt_pk_bf16_f32 v40, v44, v45
	v_cvt_pk_bf16_f32 v41, v46, v47
	v_cvt_pk_bf16_f32 v42, v48, v49
	v_cvt_pk_bf16_f32 v43, v50, v51
	s_add_u32 s24, s12, 0x2800000
	s_addc_u32 s25, s13, 0
	global_store_dwordx2 v165, v[36:37], s[24:25] offset:0
	global_store_dwordx2 v165, v[38:39], s[24:25] offset:512
	global_store_dwordx2 v165, v[40:41], s[24:25] offset:1024
	global_store_dwordx2 v165, v[42:43], s[24:25] offset:1536
	v_pk_mul_f32 v[52:53], v[52:53], v[162:163] op_sel_hi:[1,0]
	v_pk_mul_f32 v[54:55], v[54:55], v[162:163] op_sel_hi:[1,0]
	v_pk_mul_f32 v[56:57], v[56:57], v[162:163] op_sel_hi:[1,0]
	v_pk_mul_f32 v[58:59], v[58:59], v[162:163] op_sel_hi:[1,0]
	v_pk_mul_f32 v[60:61], v[60:61], v[162:163] op_sel_hi:[1,0]
	v_pk_mul_f32 v[62:63], v[62:63], v[162:163] op_sel_hi:[1,0]
	v_pk_mul_f32 v[64:65], v[64:65], v[162:163] op_sel_hi:[1,0]
	v_pk_mul_f32 v[66:67], v[66:67], v[162:163] op_sel_hi:[1,0]
	v_pk_mul_f32 v[52:53], v[52:53], v[132:133]
	v_pk_mul_f32 v[54:55], v[54:55], v[134:135]
	v_pk_mul_f32 v[56:57], v[56:57], v[136:137]
	v_pk_mul_f32 v[58:59], v[58:59], v[138:139]
	v_pk_mul_f32 v[60:61], v[60:61], v[140:141]
	v_pk_mul_f32 v[62:63], v[62:63], v[142:143]
	v_pk_mul_f32 v[64:65], v[64:65], v[144:145]
	v_pk_mul_f32 v[66:67], v[66:67], v[146:147]
	v_cvt_pk_bf16_f32 v52, v52, v53
	v_cvt_pk_bf16_f32 v53, v54, v55
	v_cvt_pk_bf16_f32 v54, v56, v57
	v_cvt_pk_bf16_f32 v55, v58, v59
	v_cvt_pk_bf16_f32 v56, v60, v61
	v_cvt_pk_bf16_f32 v57, v62, v63
	v_cvt_pk_bf16_f32 v58, v64, v65
	v_cvt_pk_bf16_f32 v59, v66, v67
	s_add_u32 s24, s12, 0x2c00000
	s_addc_u32 s25, s13, 0
	global_store_dwordx2 v165, v[52:53], s[24:25] offset:0
	global_store_dwordx2 v165, v[54:55], s[24:25] offset:512
	global_store_dwordx2 v165, v[56:57], s[24:25] offset:1024
	global_store_dwordx2 v165, v[58:59], s[24:25] offset:1536
	s_waitcnt vmcnt(28)
	v_pk_mul_f32 v[148:149], v[68:69], v[68:69]
	v_pk_fma_f32 v[148:149], v[70:71], v[70:71], v[148:149]
	v_pk_fma_f32 v[148:149], v[72:73], v[72:73], v[148:149]
	v_pk_fma_f32 v[148:149], v[74:75], v[74:75], v[148:149]
	v_pk_fma_f32 v[148:149], v[76:77], v[76:77], v[148:149]
	v_pk_fma_f32 v[148:149], v[78:79], v[78:79], v[148:149]
	v_pk_fma_f32 v[148:149], v[80:81], v[80:81], v[148:149]
	v_pk_fma_f32 v[148:149], v[82:83], v[82:83], v[148:149]
	s_waitcnt vmcnt(24)
	v_pk_mul_f32 v[150:151], v[84:85], v[84:85]
	v_pk_fma_f32 v[150:151], v[86:87], v[86:87], v[150:151]
	v_pk_fma_f32 v[150:151], v[88:89], v[88:89], v[150:151]
	v_pk_fma_f32 v[150:151], v[90:91], v[90:91], v[150:151]
	v_pk_fma_f32 v[150:151], v[92:93], v[92:93], v[150:151]
	v_pk_fma_f32 v[150:151], v[94:95], v[94:95], v[150:151]
	v_pk_fma_f32 v[150:151], v[96:97], v[96:97], v[150:151]
	v_pk_fma_f32 v[150:151], v[98:99], v[98:99], v[150:151]
	s_waitcnt vmcnt(20)
	v_pk_mul_f32 v[152:153], v[100:101], v[100:101]
	v_pk_fma_f32 v[152:153], v[102:103], v[102:103], v[152:153]
	v_pk_fma_f32 v[152:153], v[104:105], v[104:105], v[152:153]
	v_pk_fma_f32 v[152:153], v[106:107], v[106:107], v[152:153]
	v_pk_fma_f32 v[152:153], v[108:109], v[108:109], v[152:153]
	v_pk_fma_f32 v[152:153], v[110:111], v[110:111], v[152:153]
	v_pk_fma_f32 v[152:153], v[112:113], v[112:113], v[152:153]
	v_pk_fma_f32 v[152:153], v[114:115], v[114:115], v[152:153]
	s_waitcnt vmcnt(16)
	v_pk_mul_f32 v[154:155], v[116:117], v[116:117]
	v_pk_fma_f32 v[154:155], v[118:119], v[118:119], v[154:155]
	v_pk_fma_f32 v[154:155], v[120:121], v[120:121], v[154:155]
	v_pk_fma_f32 v[154:155], v[122:123], v[122:123], v[154:155]
	v_pk_fma_f32 v[154:155], v[124:125], v[124:125], v[154:155]
	v_pk_fma_f32 v[154:155], v[126:127], v[126:127], v[154:155]
	v_pk_fma_f32 v[154:155], v[128:129], v[128:129], v[154:155]
	v_pk_fma_f32 v[154:155], v[130:131], v[130:131], v[154:155]
	v_add_f32_e32 v148, v148, v149
	v_add_f32_e32 v150, v150, v151
	v_add_f32_e32 v152, v152, v153
	v_add_f32_e32 v154, v154, v155
	s_nop 0
	v_add_f32_dpp v148, v148, v148 quad_perm:[1,0,3,2] row_mask:0xf bank_mask:0xf
	v_add_f32_dpp v150, v150, v150 quad_perm:[1,0,3,2] row_mask:0xf bank_mask:0xf
	v_add_f32_dpp v152, v152, v152 quad_perm:[1,0,3,2] row_mask:0xf bank_mask:0xf
	v_add_f32_dpp v154, v154, v154 quad_perm:[1,0,3,2] row_mask:0xf bank_mask:0xf
	s_nop 0
	v_add_f32_dpp v148, v148, v148 quad_perm:[2,3,0,1] row_mask:0xf bank_mask:0xf
	v_add_f32_dpp v150, v150, v150 quad_perm:[2,3,0,1] row_mask:0xf bank_mask:0xf
	v_add_f32_dpp v152, v152, v152 quad_perm:[2,3,0,1] row_mask:0xf bank_mask:0xf
	v_add_f32_dpp v154, v154, v154 quad_perm:[2,3,0,1] row_mask:0xf bank_mask:0xf
	s_nop 0
	v_add_f32_dpp v148, v148, v148 row_half_mirror row_mask:0xf bank_mask:0xf
	v_add_f32_dpp v150, v150, v150 row_half_mirror row_mask:0xf bank_mask:0xf
	v_add_f32_dpp v152, v152, v152 row_half_mirror row_mask:0xf bank_mask:0xf
	v_add_f32_dpp v154, v154, v154 row_half_mirror row_mask:0xf bank_mask:0xf
	s_nop 0
	v_add_f32_dpp v148, v148, v148 row_mirror row_mask:0xf bank_mask:0xf
	v_add_f32_dpp v150, v150, v150 row_mirror row_mask:0xf bank_mask:0xf
	v_add_f32_dpp v152, v152, v152 row_mirror row_mask:0xf bank_mask:0xf
	v_add_f32_dpp v154, v154, v154 row_mirror row_mask:0xf bank_mask:0xf
	s_nop 0
	v_add_f32_dpp v148, v148, v148 row_bcast:15 row_mask:0xa bank_mask:0xf
	v_add_f32_dpp v150, v150, v150 row_bcast:15 row_mask:0xa bank_mask:0xf
	v_add_f32_dpp v152, v152, v152 row_bcast:15 row_mask:0xa bank_mask:0xf
	v_add_f32_dpp v154, v154, v154 row_bcast:15 row_mask:0xa bank_mask:0xf
	s_nop 0
	v_add_f32_dpp v148, v148, v148 row_bcast:31 row_mask:0xc bank_mask:0xf
	v_add_f32_dpp v150, v150, v150 row_bcast:31 row_mask:0xc bank_mask:0xf
	v_add_f32_dpp v152, v152, v152 row_bcast:31 row_mask:0xc bank_mask:0xf
	v_add_f32_dpp v154, v154, v154 row_bcast:31 row_mask:0xc bank_mask:0xf
	s_nop 1
	v_readlane_b32 s0, v148, 63
	v_readlane_b32 s1, v150, 63
	v_readlane_b32 s2, v152, 63
	v_readlane_b32 s3, v154, 63
	s_nop 1
	v_mov_b32_e32 v156, s0
	v_mov_b32_e32 v158, s1
	v_mov_b32_e32 v160, s2
	v_mov_b32_e32 v162, s3
	v_fmamk_f32 v156, v156, 0x3a800000, v196
	v_fmamk_f32 v158, v158, 0x3a800000, v196
	v_fmamk_f32 v160, v160, 0x3a800000, v196
	v_fmamk_f32 v162, v162, 0x3a800000, v196
	v_rsq_f32_e32 v156, v156
	v_rsq_f32_e32 v158, v158
	v_rsq_f32_e32 v160, v160
	v_rsq_f32_e32 v162, v162
	s_nop 0
	v_pk_mul_f32 v[68:69], v[68:69], v[156:157] op_sel_hi:[1,0]
	v_pk_mul_f32 v[70:71], v[70:71], v[156:157] op_sel_hi:[1,0]
	v_pk_mul_f32 v[72:73], v[72:73], v[156:157] op_sel_hi:[1,0]
	v_pk_mul_f32 v[74:75], v[74:75], v[156:157] op_sel_hi:[1,0]
	v_pk_mul_f32 v[76:77], v[76:77], v[156:157] op_sel_hi:[1,0]
	v_pk_mul_f32 v[78:79], v[78:79], v[156:157] op_sel_hi:[1,0]
	v_pk_mul_f32 v[80:81], v[80:81], v[156:157] op_sel_hi:[1,0]
	v_pk_mul_f32 v[82:83], v[82:83], v[156:157] op_sel_hi:[1,0]
	v_pk_mul_f32 v[68:69], v[68:69], v[132:133]
	v_pk_mul_f32 v[70:71], v[70:71], v[134:135]
	v_pk_mul_f32 v[72:73], v[72:73], v[136:137]
	v_pk_mul_f32 v[74:75], v[74:75], v[138:139]
	v_pk_mul_f32 v[76:77], v[76:77], v[140:141]
	v_pk_mul_f32 v[78:79], v[78:79], v[142:143]
	v_pk_mul_f32 v[80:81], v[80:81], v[144:145]
	v_pk_mul_f32 v[82:83], v[82:83], v[146:147]
	v_cvt_pk_bf16_f32 v68, v68, v69
	v_cvt_pk_bf16_f32 v69, v70, v71
	v_cvt_pk_bf16_f32 v70, v72, v73
	v_cvt_pk_bf16_f32 v71, v74, v75
	v_cvt_pk_bf16_f32 v72, v76, v77
	v_cvt_pk_bf16_f32 v73, v78, v79
	v_cvt_pk_bf16_f32 v74, v80, v81
	v_cvt_pk_bf16_f32 v75, v82, v83
	s_add_u32 s24, s12, 0x3000000
	s_addc_u32 s25, s13, 0
	global_store_dwordx2 v165, v[68:69], s[24:25] offset:0
	global_store_dwordx2 v165, v[70:71], s[24:25] offset:512
	global_store_dwordx2 v165, v[72:73], s[24:25] offset:1024
	global_store_dwordx2 v165, v[74:75], s[24:25] offset:1536
	v_pk_mul_f32 v[84:85], v[84:85], v[158:159] op_sel_hi:[1,0]
	v_pk_mul_f32 v[86:87], v[86:87], v[158:159] op_sel_hi:[1,0]
	v_pk_mul_f32 v[88:89], v[88:89], v[158:159] op_sel_hi:[1,0]
	v_pk_mul_f32 v[90:91], v[90:91], v[158:159] op_sel_hi:[1,0]
	v_pk_mul_f32 v[92:93], v[92:93], v[158:159] op_sel_hi:[1,0]
	v_pk_mul_f32 v[94:95], v[94:95], v[158:159] op_sel_hi:[1,0]
	v_pk_mul_f32 v[96:97], v[96:97], v[158:159] op_sel_hi:[1,0]
	v_pk_mul_f32 v[98:99], v[98:99], v[158:159] op_sel_hi:[1,0]
	v_pk_mul_f32 v[84:85], v[84:85], v[132:133]
	v_pk_mul_f32 v[86:87], v[86:87], v[134:135]
	v_pk_mul_f32 v[88:89], v[88:89], v[136:137]
	v_pk_mul_f32 v[90:91], v[90:91], v[138:139]
	v_pk_mul_f32 v[92:93], v[92:93], v[140:141]
	v_pk_mul_f32 v[94:95], v[94:95], v[142:143]
	v_pk_mul_f32 v[96:97], v[96:97], v[144:145]
	v_pk_mul_f32 v[98:99], v[98:99], v[146:147]
	v_cvt_pk_bf16_f32 v84, v84, v85
	v_cvt_pk_bf16_f32 v85, v86, v87
	v_cvt_pk_bf16_f32 v86, v88, v89
	v_cvt_pk_bf16_f32 v87, v90, v91
	v_cvt_pk_bf16_f32 v88, v92, v93
	v_cvt_pk_bf16_f32 v89, v94, v95
	v_cvt_pk_bf16_f32 v90, v96, v97
	v_cvt_pk_bf16_f32 v91, v98, v99
	s_add_u32 s24, s12, 0x3400000
	s_addc_u32 s25, s13, 0
	global_store_dwordx2 v165, v[84:85], s[24:25] offset:0
	global_store_dwordx2 v165, v[86:87], s[24:25] offset:512
	global_store_dwordx2 v165, v[88:89], s[24:25] offset:1024
	global_store_dwordx2 v165, v[90:91], s[24:25] offset:1536
	v_pk_mul_f32 v[100:101], v[100:101], v[160:161] op_sel_hi:[1,0]
	v_pk_mul_f32 v[102:103], v[102:103], v[160:161] op_sel_hi:[1,0]
	v_pk_mul_f32 v[104:105], v[104:105], v[160:161] op_sel_hi:[1,0]
	v_pk_mul_f32 v[106:107], v[106:107], v[160:161] op_sel_hi:[1,0]
	v_pk_mul_f32 v[108:109], v[108:109], v[160:161] op_sel_hi:[1,0]
	v_pk_mul_f32 v[110:111], v[110:111], v[160:161] op_sel_hi:[1,0]
	v_pk_mul_f32 v[112:113], v[112:113], v[160:161] op_sel_hi:[1,0]
	v_pk_mul_f32 v[114:115], v[114:115], v[160:161] op_sel_hi:[1,0]
	v_pk_mul_f32 v[100:101], v[100:101], v[132:133]
	v_pk_mul_f32 v[102:103], v[102:103], v[134:135]
	v_pk_mul_f32 v[104:105], v[104:105], v[136:137]
	v_pk_mul_f32 v[106:107], v[106:107], v[138:139]
	v_pk_mul_f32 v[108:109], v[108:109], v[140:141]
	v_pk_mul_f32 v[110:111], v[110:111], v[142:143]
	v_pk_mul_f32 v[112:113], v[112:113], v[144:145]
	v_pk_mul_f32 v[114:115], v[114:115], v[146:147]
	v_cvt_pk_bf16_f32 v100, v100, v101
	v_cvt_pk_bf16_f32 v101, v102, v103
	v_cvt_pk_bf16_f32 v102, v104, v105
	v_cvt_pk_bf16_f32 v103, v106, v107
	v_cvt_pk_bf16_f32 v104, v108, v109
	v_cvt_pk_bf16_f32 v105, v110, v111
	v_cvt_pk_bf16_f32 v106, v112, v113
	v_cvt_pk_bf16_f32 v107, v114, v115
	s_add_u32 s24, s12, 0x3800000
	s_addc_u32 s25, s13, 0
	global_store_dwordx2 v165, v[100:101], s[24:25] offset:0
	global_store_dwordx2 v165, v[102:103], s[24:25] offset:512
	global_store_dwordx2 v165, v[104:105], s[24:25] offset:1024
	global_store_dwordx2 v165, v[106:107], s[24:25] offset:1536
	v_pk_mul_f32 v[116:117], v[116:117], v[162:163] op_sel_hi:[1,0]
	v_pk_mul_f32 v[118:119], v[118:119], v[162:163] op_sel_hi:[1,0]
	v_pk_mul_f32 v[120:121], v[120:121], v[162:163] op_sel_hi:[1,0]
	v_pk_mul_f32 v[122:123], v[122:123], v[162:163] op_sel_hi:[1,0]
	v_pk_mul_f32 v[124:125], v[124:125], v[162:163] op_sel_hi:[1,0]
	v_pk_mul_f32 v[126:127], v[126:127], v[162:163] op_sel_hi:[1,0]
	v_pk_mul_f32 v[128:129], v[128:129], v[162:163] op_sel_hi:[1,0]
	v_pk_mul_f32 v[130:131], v[130:131], v[162:163] op_sel_hi:[1,0]
	v_pk_mul_f32 v[116:117], v[116:117], v[132:133]
	v_pk_mul_f32 v[118:119], v[118:119], v[134:135]
	v_pk_mul_f32 v[120:121], v[120:121], v[136:137]
	v_pk_mul_f32 v[122:123], v[122:123], v[138:139]
	v_pk_mul_f32 v[124:125], v[124:125], v[140:141]
	v_pk_mul_f32 v[126:127], v[126:127], v[142:143]
	v_pk_mul_f32 v[128:129], v[128:129], v[144:145]
	v_pk_mul_f32 v[130:131], v[130:131], v[146:147]
	v_cvt_pk_bf16_f32 v116, v116, v117
	v_cvt_pk_bf16_f32 v117, v118, v119
	v_cvt_pk_bf16_f32 v118, v120, v121
	v_cvt_pk_bf16_f32 v119, v122, v123
	v_cvt_pk_bf16_f32 v120, v124, v125
	v_cvt_pk_bf16_f32 v121, v126, v127
	v_cvt_pk_bf16_f32 v122, v128, v129
	v_cvt_pk_bf16_f32 v123, v130, v131
	s_add_u32 s24, s12, 0x3c00000
	s_addc_u32 s25, s13, 0
	global_store_dwordx2 v165, v[116:117], s[24:25] offset:0
	global_store_dwordx2 v165, v[118:119], s[24:25] offset:512
	global_store_dwordx2 v165, v[120:121], s[24:25] offset:1024
	global_store_dwordx2 v165, v[122:123], s[24:25] offset:1536
	s_cmpk_ge_u32 s20, 0x100
	s_cbranch_scc1 .Lrow0_done
	s_lshl_b32 s0, s20, 11
	s_add_u32 s14, s92, 0x3c00000
	s_addc_u32 s15, s93, 0
	s_add_u32 s14, s14, s0
	s_addc_u32 s15, s15, 0
	s_cmpk_ge_u32 s20, 16
	s_cbranch_scc1 .Lrow0_zero
	s_lshl_b32 s0, s20, 12
	s_add_u32 s22, s6, s0
	s_addc_u32 s23, s7, 0
	global_load_dwordx4 v[4:7], v164, s[22:23] offset:0
	global_load_dwordx4 v[8:11], v164, s[22:23] offset:1024
	global_load_dwordx4 v[12:15], v164, s[22:23] offset:2048
	global_load_dwordx4 v[16:19], v164, s[22:23] offset:3072
	s_waitcnt vmcnt(0)
	v_pk_mul_f32 v[148:149], v[4:5], v[4:5]
	v_pk_fma_f32 v[148:149], v[6:7], v[6:7], v[148:149]
	v_pk_fma_f32 v[148:149], v[8:9], v[8:9], v[148:149]
	v_pk_fma_f32 v[148:149], v[10:11], v[10:11], v[148:149]
	v_pk_fma_f32 v[148:149], v[12:13], v[12:13], v[148:149]
	v_pk_fma_f32 v[148:149], v[14:15], v[14:15], v[148:149]
	v_pk_fma_f32 v[148:149], v[16:17], v[16:17], v[148:149]
	v_pk_fma_f32 v[148:149], v[18:19], v[18:19], v[148:149]
	v_add_f32_e32 v148, v148, v149
	s_nop 1
	v_add_f32_dpp v148, v148, v148 quad_perm:[1,0,3,2] row_mask:0xf bank_mask:0xf
	s_nop 1
	v_add_f32_dpp v148, v148, v148 quad_perm:[2,3,0,1] row_mask:0xf bank_mask:0xf
	s_nop 1
	v_add_f32_dpp v148, v148, v148 row_half_mirror row_mask:0xf bank_mask:0xf
	s_nop 1
	v_add_f32_dpp v148, v148, v148 row_mirror row_mask:0xf bank_mask:0xf
	s_nop 1
	v_add_f32_dpp v148, v148, v148 row_bcast:15 row_mask:0xa bank_mask:0xf
	s_nop 1
	v_add_f32_dpp v148, v148, v148 row_bcast:31 row_mask:0xc bank_mask:0xf
	s_nop 1
	v_readlane_b32 s0, v148, 63
	s_nop 1
	v_mov_b32_e32 v156, s0
	v_fmamk_f32 v156, v156, 0x3a800000, v196
	v_rsq_f32_e32 v156, v156
	s_nop 0
	v_pk_mul_f32 v[4:5], v[4:5], v[156:157] op_sel_hi:[1,0]
	v_pk_mul_f32 v[6:7], v[6:7], v[156:157] op_sel_hi:[1,0]
	v_pk_mul_f32 v[8:9], v[8:9], v[156:157] op_sel_hi:[1,0]
	v_pk_mul_f32 v[10:11], v[10:11], v[156:157] op_sel_hi:[1,0]
	v_pk_mul_f32 v[12:13], v[12:13], v[156:157] op_sel_hi:[1,0]
	v_pk_mul_f32 v[14:15], v[14:15], v[156:157] op_sel_hi:[1,0]
	v_pk_mul_f32 v[16:17], v[16:17], v[156:157] op_sel_hi:[1,0]
	v_pk_mul_f32 v[18:19], v[18:19], v[156:157] op_sel_hi:[1,0]
	v_pk_mul_f32 v[4:5], v[4:5], v[132:133]
	v_pk_mul_f32 v[6:7], v[6:7], v[134:135]
	v_pk_mul_f32 v[8:9], v[8:9], v[136:137]
	v_pk_mul_f32 v[10:11], v[10:11], v[138:139]
	v_pk_mul_f32 v[12:13], v[12:13], v[140:141]
	v_pk_mul_f32 v[14:15], v[14:15], v[142:143]
	v_pk_mul_f32 v[16:17], v[16:17], v[144:145]
	v_pk_mul_f32 v[18:19], v[18:19], v[146:147]
	v_cvt_pk_bf16_f32 v4, v4, v5
	v_cvt_pk_bf16_f32 v5, v6, v7
	v_cvt_pk_bf16_f32 v6, v8, v9
	v_cvt_pk_bf16_f32 v7, v10, v11
	v_cvt_pk_bf16_f32 v8, v12, v13
	v_cvt_pk_bf16_f32 v9, v14, v15
	v_cvt_pk_bf16_f32 v10, v16, v17
	v_cvt_pk_bf16_f32 v11, v18, v19
	s_mov_b64 s[24:25], s[14:15]
	global_store_dwordx2 v165, v[4:5], s[24:25] offset:0
	global_store_dwordx2 v165, v[6:7], s[24:25] offset:512
	global_store_dwordx2 v165, v[8:9], s[24:25] offset:1024
	global_store_dwordx2 v165, v[10:11], s[24:25] offset:1536
	s_branch .Lrow0_done
.Lrow0_zero:
	v_mov_b32_e32 v4, 0
	v_mov_b32_e32 v5, 0
	global_store_dwordx2 v165, v[4:5], s[14:15] offset:0
	global_store_dwordx2 v165, v[4:5], s[14:15] offset:512
	global_store_dwordx2 v165, v[4:5], s[14:15] offset:1024
	global_store_dwordx2 v165, v[4:5], s[14:15] offset:1536
.Lrow0_done:
	s_mov_b64 s[44:45], exec
	s_branch .LBB0_673
.Lrow0_generic:
	s_mov_b32 s0, 0x8100
	v_cmp_gt_i32_e32 vcc, s0, v0
	s_and_saveexec_b64 s[44:45], vcc
	s_cbranch_execz .LBB0_673
	v_readlane_b32 s0, v254, 42
	v_lshlrev_b32_e32 v2, 4, v1
	v_readlane_b32 s4, v254, 46
	v_readlane_b32 s5, v254, 47
	s_nop 4
	global_load_dwordx4 v[4:7], v2, s[4:5] offset:3072
	global_load_dwordx4 v[8:11], v2, s[4:5] offset:2048
	global_load_dwordx4 v[12:15], v2, s[4:5] offset:1024
	global_load_dwordx4 v[16:19], v2, s[4:5]
	s_waitcnt vmcnt(0)
	v_lshlrev_b32_e32 v84, 2, v1
	s_lshl_b32 s20, s51, 4
	s_mul_i32 s51, s51, 24
	s_mov_b64 s[46:47], 0
	v_readlane_b32 s1, v254, 43
	v_readlane_b32 s2, v254, 44
	v_readlane_b32 s3, v254, 45
	v_readlane_b32 s6, v254, 48
	v_readlane_b32 s7, v254, 49
	v_readlane_b32 s8, v254, 50
	v_readlane_b32 s9, v254, 51
	v_readlane_b32 s10, v254, 52
	v_readlane_b32 s11, v254, 53
	v_readlane_b32 s12, v254, 54
	v_readlane_b32 s13, v254, 55
	v_readlane_b32 s14, v254, 56
	v_readlane_b32 s15, v254, 57
	s_branch .LBB0_660
